# v3 + FFN-in and ProjA epilogues: per-row ssq loads software-pipelined one tile ahead (loaded during the previous tile's epilogue)
# baseline (speedup 1.0000x reference)
; #define PG8_STAGE(bufoff, gbase, voff) do { _Pragma("unroll") for (int _i = 0; _i < 2; ++_i) \
;         __builtin_amdgcn_global_load_lds((const unsigned*)((const char*)(gbase) + (voff)[_i]), (LAS unsigned*)(lds + (bufoff) + ldsw + _i * 8192), 16, 0, 0); } while (0)
; #define PG8_WAIT_V(n) asm volatile("s_waitcnt vmcnt(" #n ")" ::: "memory")
; #define PG8_BAR __builtin_amdgcn_s_barrier()
; template <class Epi, class Sched>
; __device__ __forceinline__ void gemm_phase(int wv, LAS unsigned char* lds, const Gemm g, const Sched& S, const Epi& E) {
;     ...
;     const char* cA = (const char*)g.A + (size_t)cur.pm * tstep; const char* cB = (const char*)g.Bt + (size_t)cur.pn * tstepB;
;     PG8_STAGE(PG8_SB(0, 0), cB, voffB); PG8_STAGE(PG8_SB(0, 1), cB + hstepB, voffB); PG8_STAGE(PG8_SA(0, 0), cA, voffA); PG8_STAGE(PG8_SA(0, 1), cA + hstep, voffA);
;     if (wr == 1) PG8_BAR;
;     PG8_WAIT_V(2); PG8_BAR;
;     PG8_STAGE(PG8_SB(1, 0), cB + kstep, voffB); PG8_STAGE(PG8_SA(1, 0), cA + kstep, voffA); PG8_STAGE(PG8_SB(1, 1), cB + hstepB + kstep, voffB);
;     PG8_WAIT_V(6); PG8_BAR;
;     __device__ __forceinline__ void operator()(const AccT& acc, const Unit& u, int wr, int wc, int fr, int fq) const {
;         const int row0 = u.pm * 256 + wr * 64 + fr, col0 = u.pn * 128 + wc * 32 + 8 * fq;
;         float rsv[8];
; #pragma unroll
;         for (int idx = 0; idx < 8; ++idx) rsv[idx] = ssq[row0 + (idx >> 2) * 128 + (idx & 3) * 16];
.LBB0_172:
	v_readlane_b32 s6, v253, 32
	s_add_u32 s4, s0, 0xc100000
	v_readlane_b32 s7, v253, 33
	s_addc_u32 s5, s1, 0
	s_lshl_b64 s[6:7], s[6:7], 2
	s_add_u32 s0, s0, s6
	s_addc_u32 s1, s1, s7
	s_add_u32 s6, s0, 0x100000
	s_addc_u32 s7, s1, 0
	s_lshl_b32 s0, s10, 5
	s_and_b32 s10, s0, 0x60
	s_add_i32 m0, s29, 0x18000
	v_lshl_add_u64 v[6:7], v[6:7], 0, s[74:75]
	s_lshl_b32 s11, s9, 13
	s_lshl_b32 s12, s10, 7
	s_waitcnt vmcnt(2)
	s_barrier
	global_load_lds_dwordx4 v[6:7], off
	v_lshl_add_u64 v[4:5], v[4:5], 0, s[74:75]
	s_add_i32 m0, s29, 0x1a000
	s_add_i32 s37, s29, 0x8000
	s_add_i32 s38, s29, 0xa000
	global_load_lds_dwordx4 v[4:5], off
	v_lshl_add_u64 v[0:1], v[0:1], 0, s[74:75]
	s_mov_b32 m0, s37
	s_add_u32 s0, s20, 0x40080
	global_load_lds_dwordx4 v[0:1], off
	v_lshl_add_u64 v[0:1], v[2:3], 0, s[74:75]
	s_mov_b32 m0, s38
	s_addc_u32 s1, s21, 0
	global_load_lds_dwordx4 v[0:1], off
	s_add_i32 m0, s29, 0x1c000
	v_lshl_add_u64 v[0:1], s[0:1], 0, v[188:189]
	global_load_lds_dwordx4 v[0:1], off
	v_lshl_add_u64 v[0:1], s[0:1], 0, v[128:129]
	s_add_i32 m0, s29, 0x1e000
	s_cmpk_lt_u32 s8, 0x100
	global_load_lds_dwordx4 v[0:1], off
	v_lshrrev_b32_e32 v1, 1, v8
	v_and_b32_e32 v1, 24, v1
	v_and_b32_e32 v0, 15, v8
	v_lshlrev_b32_e32 v2, 1, v1
	v_lshl_or_b32 v142, s9, 6, v0
	v_lshl_or_b32 v0, v0, 6, v2
	v_lshlrev_b32_e32 v2, 2, v8
	v_and_b32_e32 v2, 32, v2
	v_bitop3_b32 v3, v0, s11, v2 bitop3:0xde
	v_bitop3_b32 v143, v0, s12, v2 bitop3:0xde
	v_lshlrev_b32_e32 v0, 14, v13
	v_and_b32_e32 v0, 0xffff8000, v0
	v_or_b32_e32 v144, s10, v1
	v_lshl_add_u32 v0, v12, 11, v0
	v_and_b32_e32 v1, 1, v13
	v_lshl_or_b32 v0, v1, 6, v0
	v_lshl_add_u32 v134, v14, 1, v0
	v_lshlrev_b32_e32 v0, 14, v9
	v_and_b32_e32 v0, 0xffff8000, v0
	s_waitcnt vmcnt(6)
	v_lshl_add_u32 v0, v10, 11, v0
	v_and_b32_e32 v1, 1, v9
	v_lshl_or_b32 v0, v1, 6, v0
	v_readlane_b32 s0, v252, 36
	s_cselect_b64 s[8:9], -1, 0
	v_mov_b32_e32 v135, v189
	v_lshl_add_u32 v136, v11, 1, v0
	v_mov_b32_e32 v137, v189
	s_mov_b32 s72, 0
	v_add_u32_e32 v145, 0, v3
	v_readlane_b32 s39, v252, 35
	s_mov_b32 s40, s0
	v_lshl_add_u32 v234, s40, 8, v142
	v_ashrrev_i32_e32 v235, 31, v234
	v_lshl_add_u64 v[234:235], v[234:235], 2, s[6:7]
	global_load_dword v224, v[234:235], off
	global_load_dword v227, v[234:235], off offset:64
	global_load_dword v236, v[234:235], off offset:128
	global_load_dword v239, v[234:235], off offset:192
	global_load_dword v240, v[234:235], off offset:512
	global_load_dword v241, v[234:235], off offset:576
	global_load_dword v242, v[234:235], off offset:640
	global_load_dword v243, v[234:235], off offset:704
	s_barrier
	v_readlane_b32 s1, v252, 37
	s_branch .LBB0_175

; __device__ __forceinline__ unsigned pk2(float lo, float hi) { f32x2 v = {lo, hi}; bf2_t b = __builtin_convertvector(v, bf2_t); return __builtin_bit_cast(unsigned, b); }
; __device__ __forceinline__ float siluf_(float x) { return x * sigmoidf_(x); }
;     __device__ __forceinline__ void operator()(const AccT& acc, const Unit& u, int wr, int wc, int fr, int fq) const {
;         const int row0 = u.pm * 256 + wr * 64 + fr, col0 = u.pn * 128 + wc * 32 + 8 * fq;
;         float rsv[8];
; #pragma unroll
;         for (int idx = 0; idx < 8; ++idx) rsv[idx] = ssq[row0 + (idx >> 2) * 128 + (idx & 3) * 16];
; #pragma unroll
;         for (int ai = 0; ai < 2; ++ai)
; #pragma unroll
;             for (int m = 0; m < 4; ++m) {
;                 const int row = row0 + ai * 128 + m * 16; const float rs = rsqrtf(rsv[ai * 4 + m] * (1.f / 1024.f) + EPS);
;                 float h[8];
; #pragma unroll
;                 for (int n = 0; n < 2; ++n)
; #pragma unroll
;                     for (int j = 0; j < 4; ++j) { const float a = acc[ai][0][m][n][j] * rs, b = acc[ai][1][m][n][j] * rs; h[n * 4 + j] = siluf_(a) * b; }
;                 u32x4 w; w.x = pk2(h[0], h[1]); w.y = pk2(h[2], h[3]); w.z = pk2(h[4], h[5]); w.w = pk2(h[6], h[7]);
;                 *(u32x4*)(H + (size_t)row * DFF + col0) = w;
.LBB0_181:
	v_lshl_add_u32 v138, s40, 8, v142
	v_ashrrev_i32_e32 v139, 31, v138
	v_lshl_add_u64 v[140:141], v[138:139], 2, s[6:7]
	v_lshl_or_b32 v140, s39, 7, v144
	v_ashrrev_i32_e32 v141, 31, v140
	s_movk_i32 s11, 0x1600
	v_add_u32_e32 v148, 0x80, v138
	s_waitcnt vmcnt(0)
	v_mov_b32_e32 v152, v224
	v_mov_b32_e32 v153, v227
	v_mov_b32_e32 v151, v236
	v_mov_b32_e32 v150, v239
	v_mov_b32_e32 v149, v240
	v_mov_b32_e32 v147, v241
	v_mov_b32_e32 v146, v242
	v_mov_b32_e32 v139, v243
	s_and_b32 s32, s10, 0x7f
	v_lshl_add_u32 v234, s32, 8, v142
	v_ashrrev_i32_e32 v235, 31, v234
	v_lshl_add_u64 v[234:235], v[234:235], 2, s[6:7]
	global_load_dword v224, v[234:235], off
	global_load_dword v227, v[234:235], off offset:64
	global_load_dword v236, v[234:235], off offset:128
	global_load_dword v239, v[234:235], off offset:192
	global_load_dword v240, v[234:235], off offset:512
	global_load_dword v241, v[234:235], off offset:576
	global_load_dword v242, v[234:235], off offset:640
	global_load_dword v243, v[234:235], off offset:704
	v_fmamk_f32 v152, v152, 0x3a800000, v226
	v_cmp_gt_f32_e32 vcc, s33, v152
	v_mul_f32_e32 v154, 0x4b800000, v152
	s_nop 0
	v_cndmask_b32_e32 v152, v152, v154, vcc
	v_rsq_f32_e32 v152, v152
	s_nop 0
	v_mul_f32_e32 v154, 0x45800000, v152
	v_cndmask_b32_e32 v152, v152, v154, vcc
	v_pk_mul_f32 v[124:125], v[124:125], v[152:153] op_sel_hi:[1,0]
	v_pk_mul_f32 v[116:117], v[116:117], v[152:153] op_sel_hi:[1,0]
	v_mul_f32_e32 v154, 0xbfb8aa3b, v124
	v_mul_f32_e32 v155, 0xbfb8aa3b, v125
	v_exp_f32_e32 v154, v154
	v_exp_f32_e32 v155, v155
	v_pk_mul_f32 v[118:119], v[118:119], v[152:153] op_sel_hi:[1,0]
	v_pk_mul_f32 v[120:121], v[120:121], v[152:153] op_sel_hi:[1,0]
	v_add_f32_e32 v154, 1.0, v154
	v_add_f32_e32 v155, 1.0, v155
	v_rcp_f32_e32 v154, v154
	v_rcp_f32_e32 v155, v155
	v_pk_mul_f32 v[112:113], v[112:113], v[152:153] op_sel_hi:[1,0]
	v_pk_mul_f32 v[114:115], v[114:115], v[152:153] op_sel_hi:[1,0]
	v_pk_mul_f32 v[124:125], v[124:125], v[154:155]
	s_nop 0
	v_pk_mul_f32 v[116:117], v[116:117], v[124:125]
	v_pk_mul_f32 v[124:125], v[126:127], v[152:153] op_sel_hi:[1,0]
	s_nop 0
	v_mul_f32_e32 v126, 0xbfb8aa3b, v124
	v_mul_f32_e32 v127, 0xbfb8aa3b, v125
	v_exp_f32_e32 v126, v126
	v_exp_f32_e32 v127, v127
	v_add_f32_e32 v126, 1.0, v126
	v_add_f32_e32 v127, 1.0, v127
	v_rcp_f32_e32 v126, v126
	v_rcp_f32_e32 v127, v127
	s_nop 0
	v_pk_mul_f32 v[124:125], v[124:125], v[126:127]
	s_nop 0
	v_pk_mul_f32 v[118:119], v[118:119], v[124:125]
	v_mul_f32_e32 v124, 0xbfb8aa3b, v120
	v_mul_f32_e32 v125, 0xbfb8aa3b, v121
	v_exp_f32_e32 v124, v124
	v_exp_f32_e32 v125, v125
	v_add_f32_e32 v124, 1.0, v124
	v_add_f32_e32 v125, 1.0, v125
	v_rcp_f32_e32 v124, v124
	v_rcp_f32_e32 v125, v125
	s_nop 0
	v_pk_mul_f32 v[120:121], v[120:121], v[124:125]
	s_nop 0
	v_pk_mul_f32 v[120:121], v[112:113], v[120:121]
	v_pk_mul_f32 v[112:113], v[122:123], v[152:153] op_sel_hi:[1,0]
	s_nop 0
	v_mul_f32_e32 v122, 0xbfb8aa3b, v112
	v_mul_f32_e32 v123, 0xbfb8aa3b, v113
	v_exp_f32_e32 v122, v122
	v_exp_f32_e32 v123, v123
	v_add_f32_e32 v122, 1.0, v122
	v_add_f32_e32 v123, 1.0, v123
	v_rcp_f32_e32 v122, v122
	v_rcp_f32_e32 v123, v123
	s_nop 0
	v_pk_mul_f32 v[112:113], v[112:113], v[122:123]
	s_nop 0
	v_pk_mul_f32 v[122:123], v[114:115], v[112:113]
	v_cvt_pk_bf16_f32 v112, v116, v117
	v_mov_b64_e32 v[116:117], s[4:5]
	v_cvt_pk_bf16_f32 v113, v118, v119
	v_cvt_pk_bf16_f32 v114, v120, v121
	v_mad_i64_i32 v[120:121], s[18:19], v138, s11, v[116:117]
	v_lshlrev_b64 v[118:119], 1, v[140:141]
	v_cvt_pk_bf16_f32 v115, v122, v123
	v_lshl_add_u64 v[120:121], v[120:121], 0, v[118:119]
	global_store_dwordx4 v[120:121], v[112:115], off
	s_nop 1
	v_fmamk_f32 v112, v153, 0x3a800000, v226
	v_cmp_gt_f32_e32 vcc, s33, v112
	v_mul_f32_e32 v113, 0x4b800000, v112
	s_nop 0
	v_cndmask_b32_e32 v112, v112, v113, vcc
	v_rsq_f32_e32 v112, v112
	s_nop 0
	v_mul_f32_e32 v113, 0x45800000, v112
	v_cndmask_b32_e32 v112, v112, v113, vcc
	v_pk_mul_f32 v[108:109], v[108:109], v[112:113] op_sel_hi:[1,0]
	s_nop 0
	v_mul_f32_e32 v113, 0xbfb8aa3b, v108
	v_exp_f32_e32 v113, v113
	s_nop 0
	v_add_f32_e32 v113, 1.0, v113
	v_rcp_f32_e32 v114, v113
	v_pk_mul_f32 v[104:105], v[104:105], v[112:113] op_sel_hi:[1,0]
	v_mul_f32_e32 v113, 0xbfb8aa3b, v109
	v_exp_f32_e32 v113, v113
	s_nop 0
	v_add_f32_e32 v113, 1.0, v113
	v_rcp_f32_e32 v115, v113
	v_pk_mul_f32 v[106:107], v[106:107], v[112:113] op_sel_hi:[1,0]
	v_pk_mul_f32 v[100:101], v[100:101], v[112:113] op_sel_hi:[1,0]
	v_pk_mul_f32 v[96:97], v[96:97], v[112:113] op_sel_hi:[1,0]
	v_pk_mul_f32 v[108:109], v[108:109], v[114:115]
	v_pk_mul_f32 v[98:99], v[98:99], v[112:113] op_sel_hi:[1,0]
	v_pk_mul_f32 v[104:105], v[104:105], v[108:109]
	v_pk_mul_f32 v[108:109], v[110:111], v[112:113] op_sel_hi:[1,0]
	s_nop 0
	v_mul_f32_e32 v110, 0xbfb8aa3b, v108
	v_mul_f32_e32 v111, 0xbfb8aa3b, v109
	v_exp_f32_e32 v110, v110
	v_exp_f32_e32 v111, v111
	v_add_f32_e32 v110, 1.0, v110
	v_add_f32_e32 v111, 1.0, v111
	v_rcp_f32_e32 v110, v110
	v_rcp_f32_e32 v111, v111
	s_nop 0
	v_pk_mul_f32 v[108:109], v[108:109], v[110:111]
	s_nop 0
	v_pk_mul_f32 v[106:107], v[106:107], v[108:109]
	v_mul_f32_e32 v108, 0xbfb8aa3b, v100
	v_mul_f32_e32 v109, 0xbfb8aa3b, v101
	v_exp_f32_e32 v108, v108
	v_exp_f32_e32 v109, v109
	v_add_f32_e32 v108, 1.0, v108
	v_add_f32_e32 v109, 1.0, v109
	v_rcp_f32_e32 v108, v108
	v_rcp_f32_e32 v109, v109
	s_nop 0
	v_pk_mul_f32 v[100:101], v[100:101], v[108:109]
	s_nop 0
	v_pk_mul_f32 v[100:101], v[96:97], v[100:101]
	v_pk_mul_f32 v[96:97], v[102:103], v[112:113] op_sel_hi:[1,0]
	v_or_b32_e32 v108, 16, v138
	v_mul_f32_e32 v102, 0xbfb8aa3b, v96
	v_mul_f32_e32 v103, 0xbfb8aa3b, v97
; __device__ __forceinline__ unsigned pk2(float lo, float hi) { f32x2 v = {lo, hi}; bf2_t b = __builtin_convertvector(v, bf2_t); return __builtin_bit_cast(unsigned, b); }
; __device__ __forceinline__ float siluf_(float x) { return x * sigmoidf_(x); }
;     __device__ __forceinline__ void operator()(const AccT& acc, const Unit& u, int wr, int wc, int fr, int fq) const {
;     ...
;                 const int row = row0 + ai * 128 + m * 16; const float rs = rsqrtf(rsv[ai * 4 + m] * (1.f / 1024.f) + EPS);
;                 float h[8];
; #pragma unroll
;                 for (int n = 0; n < 2; ++n)
; #pragma unroll
;                     for (int j = 0; j < 4; ++j) { const float a = acc[ai][0][m][n][j] * rs, b = acc[ai][1][m][n][j] * rs; h[n * 4 + j] = siluf_(a) * b; }
;                 u32x4 w; w.x = pk2(h[0], h[1]); w.y = pk2(h[2], h[3]); w.z = pk2(h[4], h[5]); w.w = pk2(h[6], h[7]);
;                 *(u32x4*)(H + (size_t)row * DFF + col0) = w;
	v_exp_f32_e32 v102, v102
	v_exp_f32_e32 v103, v103
	v_add_f32_e32 v102, 1.0, v102
	v_add_f32_e32 v103, 1.0, v103
	v_rcp_f32_e32 v102, v102
	v_rcp_f32_e32 v103, v103
	s_nop 0
	v_pk_mul_f32 v[96:97], v[96:97], v[102:103]
	s_nop 0
	v_pk_mul_f32 v[102:103], v[98:99], v[96:97]
	v_cvt_pk_bf16_f32 v98, v100, v101
	v_mad_i64_i32 v[100:101], s[18:19], v108, s11, v[116:117]
	v_cvt_pk_bf16_f32 v96, v104, v105
	v_cvt_pk_bf16_f32 v97, v106, v107
	v_cvt_pk_bf16_f32 v99, v102, v103
	v_lshl_add_u64 v[100:101], v[100:101], 0, v[118:119]
	global_store_dwordx4 v[100:101], v[96:99], off
	s_nop 1
	v_fmamk_f32 v96, v151, 0x3a800000, v226
	v_cmp_gt_f32_e32 vcc, s33, v96
	v_mul_f32_e32 v97, 0x4b800000, v96
	s_nop 0
	v_cndmask_b32_e32 v96, v96, v97, vcc
	v_rsq_f32_e32 v96, v96
	s_nop 0
	v_mul_f32_e32 v97, 0x45800000, v96
	v_cndmask_b32_e32 v96, v96, v97, vcc
	v_pk_mul_f32 v[92:93], v[92:93], v[96:97] op_sel_hi:[1,0]
	s_nop 0
	v_mul_f32_e32 v97, 0xbfb8aa3b, v92
	v_exp_f32_e32 v97, v97
	s_nop 0
	v_add_f32_e32 v97, 1.0, v97
	v_rcp_f32_e32 v98, v97
	v_pk_mul_f32 v[88:89], v[88:89], v[96:97] op_sel_hi:[1,0]
	v_mul_f32_e32 v97, 0xbfb8aa3b, v93
	v_exp_f32_e32 v97, v97
	s_nop 0
	v_add_f32_e32 v97, 1.0, v97
	v_rcp_f32_e32 v99, v97
	v_pk_mul_f32 v[90:91], v[90:91], v[96:97] op_sel_hi:[1,0]
	v_pk_mul_f32 v[84:85], v[84:85], v[96:97] op_sel_hi:[1,0]
	v_pk_mul_f32 v[80:81], v[80:81], v[96:97] op_sel_hi:[1,0]
	v_pk_mul_f32 v[92:93], v[92:93], v[98:99]
	v_pk_mul_f32 v[82:83], v[82:83], v[96:97] op_sel_hi:[1,0]
	v_pk_mul_f32 v[88:89], v[88:89], v[92:93]
	v_pk_mul_f32 v[92:93], v[94:95], v[96:97] op_sel_hi:[1,0]
	s_nop 0
	v_mul_f32_e32 v94, 0xbfb8aa3b, v92
	v_mul_f32_e32 v95, 0xbfb8aa3b, v93
	v_exp_f32_e32 v94, v94
	v_exp_f32_e32 v95, v95
	v_add_f32_e32 v94, 1.0, v94
	v_add_f32_e32 v95, 1.0, v95
	v_rcp_f32_e32 v94, v94
	v_rcp_f32_e32 v95, v95
	s_nop 0
	v_pk_mul_f32 v[92:93], v[92:93], v[94:95]
	s_nop 0
	v_pk_mul_f32 v[90:91], v[90:91], v[92:93]
	v_mul_f32_e32 v92, 0xbfb8aa3b, v84
	v_mul_f32_e32 v93, 0xbfb8aa3b, v85
	v_exp_f32_e32 v92, v92
	v_exp_f32_e32 v93, v93
	v_add_f32_e32 v92, 1.0, v92
	v_add_f32_e32 v93, 1.0, v93
	v_rcp_f32_e32 v92, v92
	v_rcp_f32_e32 v93, v93
	s_nop 0
	v_pk_mul_f32 v[84:85], v[84:85], v[92:93]
	s_nop 0
	v_pk_mul_f32 v[84:85], v[80:81], v[84:85]
	v_pk_mul_f32 v[80:81], v[86:87], v[96:97] op_sel_hi:[1,0]
	v_or_b32_e32 v92, 32, v138
	v_mul_f32_e32 v86, 0xbfb8aa3b, v80
	v_mul_f32_e32 v87, 0xbfb8aa3b, v81
	v_exp_f32_e32 v86, v86
	v_exp_f32_e32 v87, v87
	v_add_f32_e32 v86, 1.0, v86
	v_add_f32_e32 v87, 1.0, v87
	v_rcp_f32_e32 v86, v86
	v_rcp_f32_e32 v87, v87
	s_nop 0
	v_pk_mul_f32 v[80:81], v[80:81], v[86:87]
	s_nop 0
	v_pk_mul_f32 v[86:87], v[82:83], v[80:81]
	v_cvt_pk_bf16_f32 v82, v84, v85
	v_mad_i64_i32 v[84:85], s[18:19], v92, s11, v[116:117]
	v_cvt_pk_bf16_f32 v80, v88, v89
	v_cvt_pk_bf16_f32 v81, v90, v91
	v_cvt_pk_bf16_f32 v83, v86, v87
	v_lshl_add_u64 v[84:85], v[84:85], 0, v[118:119]
	global_store_dwordx4 v[84:85], v[80:83], off
	s_nop 1
	v_fmamk_f32 v80, v150, 0x3a800000, v226
	v_cmp_gt_f32_e32 vcc, s33, v80
	v_mul_f32_e32 v81, 0x4b800000, v80
	s_nop 0
	v_cndmask_b32_e32 v80, v80, v81, vcc
	v_rsq_f32_e32 v80, v80
	s_nop 0
	v_mul_f32_e32 v81, 0x45800000, v80
	v_cndmask_b32_e32 v80, v80, v81, vcc
	v_pk_mul_f32 v[76:77], v[76:77], v[80:81] op_sel_hi:[1,0]
	s_nop 0
	v_mul_f32_e32 v81, 0xbfb8aa3b, v76
	v_exp_f32_e32 v81, v81
	s_nop 0
	v_add_f32_e32 v81, 1.0, v81
	v_rcp_f32_e32 v82, v81
	v_pk_mul_f32 v[72:73], v[72:73], v[80:81] op_sel_hi:[1,0]
	v_mul_f32_e32 v81, 0xbfb8aa3b, v77
	v_exp_f32_e32 v81, v81
	s_nop 0
	v_add_f32_e32 v81, 1.0, v81
	v_rcp_f32_e32 v83, v81
	v_pk_mul_f32 v[74:75], v[74:75], v[80:81] op_sel_hi:[1,0]
	v_pk_mul_f32 v[68:69], v[68:69], v[80:81] op_sel_hi:[1,0]
	v_pk_mul_f32 v[64:65], v[64:65], v[80:81] op_sel_hi:[1,0]
	v_pk_mul_f32 v[76:77], v[76:77], v[82:83]
	v_pk_mul_f32 v[66:67], v[66:67], v[80:81] op_sel_hi:[1,0]
	v_pk_mul_f32 v[72:73], v[72:73], v[76:77]
	v_pk_mul_f32 v[76:77], v[78:79], v[80:81] op_sel_hi:[1,0]
	s_nop 0
	v_mul_f32_e32 v78, 0xbfb8aa3b, v76
	v_mul_f32_e32 v79, 0xbfb8aa3b, v77
	v_exp_f32_e32 v78, v78
	v_exp_f32_e32 v79, v79
	v_add_f32_e32 v78, 1.0, v78
	v_add_f32_e32 v79, 1.0, v79
	v_rcp_f32_e32 v78, v78
	v_rcp_f32_e32 v79, v79
	s_nop 0
	v_pk_mul_f32 v[76:77], v[76:77], v[78:79]
	s_nop 0
	v_pk_mul_f32 v[74:75], v[74:75], v[76:77]
	v_mul_f32_e32 v76, 0xbfb8aa3b, v68
	v_mul_f32_e32 v77, 0xbfb8aa3b, v69
	v_exp_f32_e32 v76, v76
	v_exp_f32_e32 v77, v77
	v_add_f32_e32 v76, 1.0, v76
	v_add_f32_e32 v77, 1.0, v77
	v_rcp_f32_e32 v76, v76
	v_rcp_f32_e32 v77, v77
	s_nop 0
	v_pk_mul_f32 v[68:69], v[68:69], v[76:77]
	s_nop 0
	v_pk_mul_f32 v[68:69], v[64:65], v[68:69]
	v_pk_mul_f32 v[64:65], v[70:71], v[80:81] op_sel_hi:[1,0]
	v_or_b32_e32 v76, 48, v138
	v_mul_f32_e32 v70, 0xbfb8aa3b, v64
	v_mul_f32_e32 v71, 0xbfb8aa3b, v65
	v_exp_f32_e32 v70, v70
	v_exp_f32_e32 v71, v71
	v_add_f32_e32 v70, 1.0, v70
	v_add_f32_e32 v71, 1.0, v71
	v_rcp_f32_e32 v70, v70
	v_rcp_f32_e32 v71, v71
	s_nop 0
	v_pk_mul_f32 v[64:65], v[64:65], v[70:71]
	s_nop 0
	v_pk_mul_f32 v[70:71], v[66:67], v[64:65]
	v_cvt_pk_bf16_f32 v66, v68, v69
	v_mad_i64_i32 v[68:69], s[18:19], v76, s11, v[116:117]
	v_cvt_pk_bf16_f32 v64, v72, v73
	v_cvt_pk_bf16_f32 v65, v74, v75
	v_cvt_pk_bf16_f32 v67, v70, v71
	v_lshl_add_u64 v[68:69], v[68:69], 0, v[118:119]
	global_store_dwordx4 v[68:69], v[64:67], off
	s_nop 1
	v_fmamk_f32 v64, v149, 0x3a800000, v226
	v_cmp_gt_f32_e32 vcc, s33, v64
	v_mul_f32_e32 v65, 0x4b800000, v64
	s_nop 0
	v_cndmask_b32_e32 v64, v64, v65, vcc
	v_rsq_f32_e32 v64, v64
	s_nop 0
	v_mul_f32_e32 v65, 0x45800000, v64
	v_cndmask_b32_e32 v64, v64, v65, vcc
; __device__ __forceinline__ unsigned pk2(float lo, float hi) { f32x2 v = {lo, hi}; bf2_t b = __builtin_convertvector(v, bf2_t); return __builtin_bit_cast(unsigned, b); }
; __device__ __forceinline__ float siluf_(float x) { return x * sigmoidf_(x); }
;     __device__ __forceinline__ void operator()(const AccT& acc, const Unit& u, int wr, int wc, int fr, int fq) const {
;     ...
;                 const int row = row0 + ai * 128 + m * 16; const float rs = rsqrtf(rsv[ai * 4 + m] * (1.f / 1024.f) + EPS);
;                 float h[8];
; #pragma unroll
;                 for (int n = 0; n < 2; ++n)
; #pragma unroll
;                     for (int j = 0; j < 4; ++j) { const float a = acc[ai][0][m][n][j] * rs, b = acc[ai][1][m][n][j] * rs; h[n * 4 + j] = siluf_(a) * b; }
;                 u32x4 w; w.x = pk2(h[0], h[1]); w.y = pk2(h[2], h[3]); w.z = pk2(h[4], h[5]); w.w = pk2(h[6], h[7]);
;                 *(u32x4*)(H + (size_t)row * DFF + col0) = w;
	v_pk_mul_f32 v[60:61], v[60:61], v[64:65] op_sel_hi:[1,0]
	s_nop 0
	v_mul_f32_e32 v65, 0xbfb8aa3b, v60
	v_exp_f32_e32 v65, v65
	s_nop 0
	v_add_f32_e32 v65, 1.0, v65
	v_rcp_f32_e32 v66, v65
	v_pk_mul_f32 v[56:57], v[56:57], v[64:65] op_sel_hi:[1,0]
	v_mul_f32_e32 v65, 0xbfb8aa3b, v61
	v_exp_f32_e32 v65, v65
	s_nop 0
	v_add_f32_e32 v65, 1.0, v65
	v_rcp_f32_e32 v67, v65
	v_pk_mul_f32 v[58:59], v[58:59], v[64:65] op_sel_hi:[1,0]
	v_pk_mul_f32 v[52:53], v[52:53], v[64:65] op_sel_hi:[1,0]
	v_pk_mul_f32 v[48:49], v[48:49], v[64:65] op_sel_hi:[1,0]
	v_pk_mul_f32 v[60:61], v[60:61], v[66:67]
	v_pk_mul_f32 v[50:51], v[50:51], v[64:65] op_sel_hi:[1,0]
	v_pk_mul_f32 v[56:57], v[56:57], v[60:61]
	v_pk_mul_f32 v[60:61], v[62:63], v[64:65] op_sel_hi:[1,0]
	s_nop 0
	v_mul_f32_e32 v62, 0xbfb8aa3b, v60
	v_mul_f32_e32 v63, 0xbfb8aa3b, v61
	v_exp_f32_e32 v62, v62
	v_exp_f32_e32 v63, v63
	v_add_f32_e32 v62, 1.0, v62
	v_add_f32_e32 v63, 1.0, v63
	v_rcp_f32_e32 v62, v62
	v_rcp_f32_e32 v63, v63
	s_nop 0
	v_pk_mul_f32 v[60:61], v[60:61], v[62:63]
	s_nop 0
	v_pk_mul_f32 v[58:59], v[58:59], v[60:61]
	v_mul_f32_e32 v60, 0xbfb8aa3b, v52
	v_mul_f32_e32 v61, 0xbfb8aa3b, v53
	v_exp_f32_e32 v60, v60
	v_exp_f32_e32 v61, v61
	v_add_f32_e32 v60, 1.0, v60
	v_add_f32_e32 v61, 1.0, v61
	v_rcp_f32_e32 v60, v60
	v_rcp_f32_e32 v61, v61
	s_nop 0
	v_pk_mul_f32 v[52:53], v[52:53], v[60:61]
	s_nop 0
	v_pk_mul_f32 v[52:53], v[48:49], v[52:53]
	v_pk_mul_f32 v[48:49], v[54:55], v[64:65] op_sel_hi:[1,0]
	s_nop 0
	v_mul_f32_e32 v54, 0xbfb8aa3b, v48
	v_mul_f32_e32 v55, 0xbfb8aa3b, v49
	v_exp_f32_e32 v54, v54
	v_exp_f32_e32 v55, v55
	v_add_f32_e32 v54, 1.0, v54
	v_add_f32_e32 v55, 1.0, v55
	v_rcp_f32_e32 v54, v54
	v_rcp_f32_e32 v55, v55
	s_nop 0
	v_pk_mul_f32 v[48:49], v[48:49], v[54:55]
	s_nop 0
	v_pk_mul_f32 v[54:55], v[50:51], v[48:49]
	v_cvt_pk_bf16_f32 v50, v52, v53
	v_mad_i64_i32 v[52:53], s[18:19], v148, s11, v[116:117]
	v_cvt_pk_bf16_f32 v48, v56, v57
	v_cvt_pk_bf16_f32 v49, v58, v59
	v_cvt_pk_bf16_f32 v51, v54, v55
	v_lshl_add_u64 v[52:53], v[52:53], 0, v[118:119]
	global_store_dwordx4 v[52:53], v[48:51], off
	s_nop 1
	v_fmamk_f32 v48, v147, 0x3a800000, v226
	v_cmp_gt_f32_e32 vcc, s33, v48
	v_mul_f32_e32 v49, 0x4b800000, v48
	s_nop 0
	v_cndmask_b32_e32 v48, v48, v49, vcc
	v_rsq_f32_e32 v48, v48
	s_nop 0
	v_mul_f32_e32 v49, 0x45800000, v48
	v_cndmask_b32_e32 v48, v48, v49, vcc
	v_pk_mul_f32 v[44:45], v[44:45], v[48:49] op_sel_hi:[1,0]
	s_nop 0
	v_mul_f32_e32 v49, 0xbfb8aa3b, v44
	v_exp_f32_e32 v49, v49
	s_nop 0
	v_add_f32_e32 v49, 1.0, v49
	v_rcp_f32_e32 v50, v49
	v_pk_mul_f32 v[40:41], v[40:41], v[48:49] op_sel_hi:[1,0]
	v_mul_f32_e32 v49, 0xbfb8aa3b, v45
	v_exp_f32_e32 v49, v49
	s_nop 0
	v_add_f32_e32 v49, 1.0, v49
	v_rcp_f32_e32 v51, v49
	v_pk_mul_f32 v[42:43], v[42:43], v[48:49] op_sel_hi:[1,0]
	v_pk_mul_f32 v[36:37], v[36:37], v[48:49] op_sel_hi:[1,0]
	v_pk_mul_f32 v[32:33], v[32:33], v[48:49] op_sel_hi:[1,0]
	v_pk_mul_f32 v[44:45], v[44:45], v[50:51]
	v_pk_mul_f32 v[34:35], v[34:35], v[48:49] op_sel_hi:[1,0]
	v_pk_mul_f32 v[40:41], v[40:41], v[44:45]
	v_pk_mul_f32 v[44:45], v[46:47], v[48:49] op_sel_hi:[1,0]
	s_nop 0
	v_mul_f32_e32 v46, 0xbfb8aa3b, v44
	v_mul_f32_e32 v47, 0xbfb8aa3b, v45
	v_exp_f32_e32 v46, v46
	v_exp_f32_e32 v47, v47
	v_add_f32_e32 v46, 1.0, v46
	v_add_f32_e32 v47, 1.0, v47
	v_rcp_f32_e32 v46, v46
	v_rcp_f32_e32 v47, v47
	s_nop 0
	v_pk_mul_f32 v[44:45], v[44:45], v[46:47]
	s_nop 0
	v_pk_mul_f32 v[42:43], v[42:43], v[44:45]
	v_mul_f32_e32 v44, 0xbfb8aa3b, v36
	v_mul_f32_e32 v45, 0xbfb8aa3b, v37
	v_exp_f32_e32 v44, v44
	v_exp_f32_e32 v45, v45
	v_add_f32_e32 v44, 1.0, v44
	v_add_f32_e32 v45, 1.0, v45
	v_rcp_f32_e32 v44, v44
	v_rcp_f32_e32 v45, v45
	s_nop 0
	v_pk_mul_f32 v[36:37], v[36:37], v[44:45]
	s_nop 0
	v_pk_mul_f32 v[36:37], v[32:33], v[36:37]
	v_pk_mul_f32 v[32:33], v[38:39], v[48:49] op_sel_hi:[1,0]
	v_add_u32_e32 v44, 0x90, v138
	v_mul_f32_e32 v38, 0xbfb8aa3b, v32
	v_mul_f32_e32 v39, 0xbfb8aa3b, v33
	v_exp_f32_e32 v38, v38
	v_exp_f32_e32 v39, v39
	v_add_f32_e32 v38, 1.0, v38
	v_add_f32_e32 v39, 1.0, v39
	v_rcp_f32_e32 v38, v38
	v_rcp_f32_e32 v39, v39
	s_nop 0
	v_pk_mul_f32 v[32:33], v[32:33], v[38:39]
	s_nop 0
	v_pk_mul_f32 v[38:39], v[34:35], v[32:33]
	v_cvt_pk_bf16_f32 v34, v36, v37
	v_mad_i64_i32 v[36:37], s[18:19], v44, s11, v[116:117]
	v_cvt_pk_bf16_f32 v32, v40, v41
	v_cvt_pk_bf16_f32 v33, v42, v43
	v_cvt_pk_bf16_f32 v35, v38, v39
	v_lshl_add_u64 v[36:37], v[36:37], 0, v[118:119]
	global_store_dwordx4 v[36:37], v[32:35], off
	s_nop 1
	v_fmamk_f32 v32, v146, 0x3a800000, v226
	v_cmp_gt_f32_e32 vcc, s33, v32
	v_mul_f32_e32 v33, 0x4b800000, v32
	s_nop 0
	v_cndmask_b32_e32 v32, v32, v33, vcc
	v_rsq_f32_e32 v32, v32
; __device__ __forceinline__ unsigned pk2(float lo, float hi) { f32x2 v = {lo, hi}; bf2_t b = __builtin_convertvector(v, bf2_t); return __builtin_bit_cast(unsigned, b); }
; __device__ __forceinline__ float siluf_(float x) { return x * sigmoidf_(x); }
; #define PG8_BAR __builtin_amdgcn_s_barrier()
; template <class Epi, class Sched>
; __device__ __forceinline__ void gemm_phase(int wv, LAS unsigned char* lds, const Gemm g, const Sched& S, const Epi& E) {
;     ...
;         if (!has_next) break;
; #pragma unroll
;         for (int a = 0; a < 2; ++a)
; #pragma unroll
;             for (int b = 0; b < 2; ++b)
; #pragma unroll
;                 for (int m = 0; m < 4; ++m)
; #pragma unroll
;                     for (int n = 0; n < 2; ++n) acc[a][b][m][n] = (f32x4){0.f, 0.f, 0.f, 0.f};
;         cur = nxt; cA = nA; cB = nB; ++ui;
;         if (wr == 1) PG8_BAR;
;     __device__ __forceinline__ void operator()(const AccT& acc, const Unit& u, int wr, int wc, int fr, int fq) const {
;     ...
;                 const int row = row0 + ai * 128 + m * 16; const float rs = rsqrtf(rsv[ai * 4 + m] * (1.f / 1024.f) + EPS);
;                 float h[8];
; #pragma unroll
;                 for (int n = 0; n < 2; ++n)
; #pragma unroll
;                     for (int j = 0; j < 4; ++j) { const float a = acc[ai][0][m][n][j] * rs, b = acc[ai][1][m][n][j] * rs; h[n * 4 + j] = siluf_(a) * b; }
;                 u32x4 w; w.x = pk2(h[0], h[1]); w.y = pk2(h[2], h[3]); w.z = pk2(h[4], h[5]); w.w = pk2(h[6], h[7]);
;                 *(u32x4*)(H + (size_t)row * DFF + col0) = w;
	s_nop 0
	v_mul_f32_e32 v33, 0x45800000, v32
	v_cndmask_b32_e32 v32, v32, v33, vcc
	v_pk_mul_f32 v[28:29], v[28:29], v[32:33] op_sel_hi:[1,0]
	s_nop 0
	v_mul_f32_e32 v33, 0xbfb8aa3b, v28
	v_exp_f32_e32 v33, v33
	s_nop 0
	v_add_f32_e32 v33, 1.0, v33
	v_rcp_f32_e32 v34, v33
	v_pk_mul_f32 v[24:25], v[24:25], v[32:33] op_sel_hi:[1,0]
	v_mul_f32_e32 v33, 0xbfb8aa3b, v29
	v_exp_f32_e32 v33, v33
	s_nop 0
	v_add_f32_e32 v33, 1.0, v33
	v_rcp_f32_e32 v35, v33
	v_pk_mul_f32 v[26:27], v[26:27], v[32:33] op_sel_hi:[1,0]
	v_pk_mul_f32 v[20:21], v[20:21], v[32:33] op_sel_hi:[1,0]
	v_pk_mul_f32 v[16:17], v[16:17], v[32:33] op_sel_hi:[1,0]
	v_pk_mul_f32 v[28:29], v[28:29], v[34:35]
	v_pk_mul_f32 v[18:19], v[18:19], v[32:33] op_sel_hi:[1,0]
	v_pk_mul_f32 v[24:25], v[24:25], v[28:29]
	v_pk_mul_f32 v[28:29], v[30:31], v[32:33] op_sel_hi:[1,0]
	s_nop 0
	v_mul_f32_e32 v30, 0xbfb8aa3b, v28
	v_mul_f32_e32 v31, 0xbfb8aa3b, v29
	v_exp_f32_e32 v30, v30
	v_exp_f32_e32 v31, v31
	v_add_f32_e32 v30, 1.0, v30
	v_add_f32_e32 v31, 1.0, v31
	v_rcp_f32_e32 v30, v30
	v_rcp_f32_e32 v31, v31
	s_nop 0
	v_pk_mul_f32 v[28:29], v[28:29], v[30:31]
	s_nop 0
	v_pk_mul_f32 v[26:27], v[26:27], v[28:29]
	v_mul_f32_e32 v28, 0xbfb8aa3b, v20
	v_mul_f32_e32 v29, 0xbfb8aa3b, v21
	v_exp_f32_e32 v28, v28
	v_exp_f32_e32 v29, v29
	v_add_f32_e32 v28, 1.0, v28
	v_add_f32_e32 v29, 1.0, v29
	v_rcp_f32_e32 v28, v28
	v_rcp_f32_e32 v29, v29
	s_nop 0
	v_pk_mul_f32 v[20:21], v[20:21], v[28:29]
	s_nop 0
	v_pk_mul_f32 v[20:21], v[16:17], v[20:21]
	v_pk_mul_f32 v[16:17], v[22:23], v[32:33] op_sel_hi:[1,0]
	v_add_u32_e32 v28, 0xa0, v138
	v_mul_f32_e32 v22, 0xbfb8aa3b, v16
	v_mul_f32_e32 v23, 0xbfb8aa3b, v17
	v_exp_f32_e32 v22, v22
	v_exp_f32_e32 v23, v23
	v_add_f32_e32 v22, 1.0, v22
	v_add_f32_e32 v23, 1.0, v23
	v_rcp_f32_e32 v22, v22
	v_rcp_f32_e32 v23, v23
	s_nop 0
	v_pk_mul_f32 v[16:17], v[16:17], v[22:23]
	s_nop 0
	v_pk_mul_f32 v[22:23], v[18:19], v[16:17]
	v_cvt_pk_bf16_f32 v18, v20, v21
	v_mad_i64_i32 v[20:21], s[18:19], v28, s11, v[116:117]
	v_cvt_pk_bf16_f32 v16, v24, v25
	v_cvt_pk_bf16_f32 v17, v26, v27
	v_cvt_pk_bf16_f32 v19, v22, v23
	v_lshl_add_u64 v[20:21], v[20:21], 0, v[118:119]
	global_store_dwordx4 v[20:21], v[16:19], off
	s_nop 1
	v_fmamk_f32 v16, v139, 0x3a800000, v226
	v_cmp_gt_f32_e32 vcc, s33, v16
	v_mul_f32_e32 v17, 0x4b800000, v16
	s_nop 0
	v_cndmask_b32_e32 v16, v16, v17, vcc
	v_rsq_f32_e32 v16, v16
	s_nop 0
	v_mul_f32_e32 v17, 0x45800000, v16
	v_cndmask_b32_e32 v16, v16, v17, vcc
	v_pk_mul_f32 v[12:13], v[12:13], v[16:17] op_sel_hi:[1,0]
	s_andn2_b64 vcc, exec, s[0:1]
	v_mul_f32_e32 v17, 0xbfb8aa3b, v12
	v_exp_f32_e32 v17, v17
	s_nop 0
	v_add_f32_e32 v17, 1.0, v17
	v_rcp_f32_e32 v18, v17
	v_pk_mul_f32 v[8:9], v[8:9], v[16:17] op_sel_hi:[1,0]
	v_mul_f32_e32 v17, 0xbfb8aa3b, v13
	v_exp_f32_e32 v17, v17
	s_nop 0
	v_add_f32_e32 v17, 1.0, v17
	v_rcp_f32_e32 v19, v17
	v_pk_mul_f32 v[10:11], v[10:11], v[16:17] op_sel_hi:[1,0]
	v_pk_mul_f32 v[4:5], v[4:5], v[16:17] op_sel_hi:[1,0]
	v_pk_mul_f32 v[0:1], v[0:1], v[16:17] op_sel_hi:[1,0]
	v_pk_mul_f32 v[12:13], v[12:13], v[18:19]
	v_pk_mul_f32 v[2:3], v[2:3], v[16:17] op_sel_hi:[1,0]
	v_pk_mul_f32 v[8:9], v[8:9], v[12:13]
	v_pk_mul_f32 v[12:13], v[14:15], v[16:17] op_sel_hi:[1,0]
	s_nop 0
	v_mul_f32_e32 v14, 0xbfb8aa3b, v12
	v_mul_f32_e32 v15, 0xbfb8aa3b, v13
	v_exp_f32_e32 v14, v14
	v_exp_f32_e32 v15, v15
	v_add_f32_e32 v14, 1.0, v14
	v_add_f32_e32 v15, 1.0, v15
	v_rcp_f32_e32 v14, v14
	v_rcp_f32_e32 v15, v15
	s_nop 0
	v_pk_mul_f32 v[12:13], v[12:13], v[14:15]
	s_nop 0
	v_pk_mul_f32 v[10:11], v[10:11], v[12:13]
	v_mul_f32_e32 v12, 0xbfb8aa3b, v4
	v_mul_f32_e32 v13, 0xbfb8aa3b, v5
	v_exp_f32_e32 v12, v12
	v_exp_f32_e32 v13, v13
	v_add_f32_e32 v12, 1.0, v12
	v_add_f32_e32 v13, 1.0, v13
	v_rcp_f32_e32 v12, v12
	v_rcp_f32_e32 v13, v13
	s_nop 0
	v_pk_mul_f32 v[4:5], v[4:5], v[12:13]
	s_nop 0
	v_pk_mul_f32 v[4:5], v[0:1], v[4:5]
	v_pk_mul_f32 v[0:1], v[6:7], v[16:17] op_sel_hi:[1,0]
	v_add_u32_e32 v12, 0xb0, v138
	v_mul_f32_e32 v6, 0xbfb8aa3b, v0
	v_mul_f32_e32 v7, 0xbfb8aa3b, v1
	v_exp_f32_e32 v6, v6
	v_exp_f32_e32 v7, v7
	v_add_f32_e32 v6, 1.0, v6
	v_add_f32_e32 v7, 1.0, v7
	v_rcp_f32_e32 v6, v6
	v_rcp_f32_e32 v7, v7
	s_nop 0
	v_pk_mul_f32 v[0:1], v[0:1], v[6:7]
	s_nop 0
	v_pk_mul_f32 v[6:7], v[2:3], v[0:1]
	v_cvt_pk_bf16_f32 v2, v4, v5
	v_mad_i64_i32 v[4:5], s[18:19], v12, s11, v[116:117]
	v_cvt_pk_bf16_f32 v0, v8, v9
	v_cvt_pk_bf16_f32 v1, v10, v11
	v_cvt_pk_bf16_f32 v3, v6, v7
	v_lshl_add_u64 v[4:5], v[4:5], 0, v[118:119]
	s_mov_b64 s[18:19], -1
	global_store_dwordx4 v[4:5], v[0:3], off
	s_cbranch_vccnz .LBB0_174
	s_andn2_b64 vcc, exec, s[2:3]
	s_cbranch_vccnz .LBB0_173
	s_barrier
	s_branch .LBB0_173

; #define PG8_STAGE(bufoff, gbase, voff) do { _Pragma("unroll") for (int _i = 0; _i < 2; ++_i) \
;         __builtin_amdgcn_global_load_lds((const unsigned*)((const char*)(gbase) + (voff)[_i]), (LAS unsigned*)(lds + (bufoff) + ldsw + _i * 8192), 16, 0, 0); } while (0)
; #define PG8_WAIT_V(n) asm volatile("s_waitcnt vmcnt(" #n ")" ::: "memory")
; #define PG8_BAR __builtin_amdgcn_s_barrier()
; template <class Epi, class Sched>
; __device__ __forceinline__ void gemm_phase(int wv, LAS unsigned char* lds, const Gemm g, const Sched& S, const Epi& E) {
;     ...
;     const char* cA = (const char*)g.A + (size_t)cur.pm * tstep; const char* cB = (const char*)g.Bt + (size_t)cur.pn * tstepB;
;     PG8_STAGE(PG8_SB(0, 0), cB, voffB); PG8_STAGE(PG8_SB(0, 1), cB + hstepB, voffB); PG8_STAGE(PG8_SA(0, 0), cA, voffA); PG8_STAGE(PG8_SA(0, 1), cA + hstep, voffA);
;     if (wr == 1) PG8_BAR;
;     PG8_WAIT_V(2); PG8_BAR;
;     PG8_STAGE(PG8_SB(1, 0), cB + kstep, voffB); PG8_STAGE(PG8_SA(1, 0), cA + kstep, voffA); PG8_STAGE(PG8_SB(1, 1), cB + hstepB + kstep, voffB);
;     PG8_WAIT_V(6); PG8_BAR;
;     __device__ __forceinline__ void operator()(const AccT& acc, const Unit& u, int wr, int wc, int fr, int fq) const {
;         const int seg = u.pn >> 2; const bool act = (seg == 0) || (seg == 3);
;         bf16_t* base = O + (size_t)seg * ((size_t)MTOK * DM);
;         const int row0 = u.pm * 256 + wr * 64 + fr, col0 = (u.pn & 3) * 256 + wc * 64 + 16 * fq;
;         float rsv[8];
; #pragma unroll
;         for (int idx = 0; idx < 8; ++idx) rsv[idx] = ssq[row0 + (idx >> 2) * 128 + (idx & 3) * 16];
.LBB0_334:
	v_readlane_b32 s6, v253, 32
	v_readlane_b32 s7, v253, 33
	s_lshl_b64 s[6:7], s[6:7], 2
	s_add_u32 s6, s0, s6
	s_addc_u32 s7, s1, s7
	s_add_u32 s6, s6, 0x120000
	s_addc_u32 s7, s7, 0
	s_add_u32 s31, s0, 0xc100000
	s_addc_u32 s36, s1, 0
	s_and_b32 s10, s10, 3
	s_add_i32 m0, s27, 0x18000
	v_lshl_add_u64 v[6:7], v[6:7], 0, s[74:75]
	s_lshl_b32 s11, s9, 13
	s_lshl_b32 s12, s10, 12
	s_waitcnt vmcnt(2)
	s_barrier
	global_load_lds_dwordx4 v[6:7], off
	v_lshl_add_u64 v[4:5], v[4:5], 0, s[74:75]
	s_add_i32 m0, s27, 0x1a000
	s_add_i32 s37, s27, 0x8000
	s_add_i32 s38, s27, 0xa000
	global_load_lds_dwordx4 v[4:5], off
	v_lshl_add_u64 v[0:1], v[0:1], 0, s[74:75]
	s_mov_b32 m0, s37
	s_add_u32 s0, s18, 0x4080
	global_load_lds_dwordx4 v[0:1], off
	v_lshl_add_u64 v[0:1], v[2:3], 0, s[74:75]
	s_mov_b32 m0, s38
	s_addc_u32 s1, s19, 0
	global_load_lds_dwordx4 v[0:1], off
	s_add_i32 m0, s27, 0x1c000
	v_lshl_add_u64 v[0:1], s[0:1], 0, v[132:133]
	global_load_lds_dwordx4 v[0:1], off
	v_lshl_add_u64 v[0:1], s[0:1], 0, v[128:129]
	s_add_i32 m0, s27, 0x1e000
	v_lshlrev_b32_e32 v2, 2, v8
	global_load_lds_dwordx4 v[0:1], off
	v_and_b32_e32 v0, 15, v8
	v_and_b32_e32 v1, 48, v8
	v_lshl_or_b32 v144, s9, 6, v0
	v_lshl_or_b32 v0, v0, 6, v1
	v_and_b32_e32 v2, 32, v2
	v_bitop3_b32 v3, v0, s11, v2 bitop3:0xde
	v_bitop3_b32 v145, v0, s12, v2 bitop3:0xde
	v_lshlrev_b32_e32 v0, 14, v13
	v_and_b32_e32 v0, 0xffff8000, v0
	v_lshl_or_b32 v146, s10, 6, v1
	v_lshl_add_u32 v0, v12, 11, v0
	v_and_b32_e32 v1, 1, v13
	v_lshl_or_b32 v0, v1, 6, v0
	v_lshl_add_u32 v136, v14, 1, v0
	v_lshlrev_b32_e32 v0, 14, v9
	v_and_b32_e32 v0, 0xffff8000, v0
	s_waitcnt vmcnt(6)
	v_lshl_add_u32 v0, v10, 11, v0
	v_and_b32_e32 v1, 1, v9
	s_cmpk_lt_u32 s8, 0x100
	v_lshl_or_b32 v0, v1, 6, v0
	v_readlane_b32 s0, v252, 43
	s_cselect_b64 s[8:9], -1, 0
	v_mov_b32_e32 v137, v189
	v_lshl_add_u32 v138, v11, 1, v0
	v_mov_b32_e32 v139, v189
	s_mov_b32 s72, 0
	v_add_u32_e32 v147, 0, v3
	v_readlane_b32 s39, v252, 42
	s_mov_b32 s40, s0
	v_lshl_add_u32 v232, s40, 8, v144
	v_ashrrev_i32_e32 v233, 31, v232
	v_lshl_add_u64 v[232:233], v[232:233], 2, s[6:7]
	global_load_dword v224, v[232:233], off
	global_load_dword v227, v[232:233], off offset:64
	global_load_dword v234, v[232:233], off offset:128
	global_load_dword v235, v[232:233], off offset:192
	global_load_dword v236, v[232:233], off offset:512
	global_load_dword v239, v[232:233], off offset:576
	global_load_dword v240, v[232:233], off offset:640
	global_load_dword v241, v[232:233], off offset:704
	s_barrier
	v_readlane_b32 s1, v252, 44
	s_branch .LBB0_337

; __device__ __forceinline__ unsigned pk2(float lo, float hi) { f32x2 v = {lo, hi}; bf2_t b = __builtin_convertvector(v, bf2_t); return __builtin_bit_cast(unsigned, b); }
; __device__ __forceinline__ float siluf_(float x) { return x * sigmoidf_(x); }
;     __device__ __forceinline__ void operator()(const AccT& acc, const Unit& u, int wr, int wc, int fr, int fq) const {
;         const int seg = u.pn >> 2; const bool act = (seg == 0) || (seg == 3);
;         bf16_t* base = O + (size_t)seg * ((size_t)MTOK * DM);
;         const int row0 = u.pm * 256 + wr * 64 + fr, col0 = (u.pn & 3) * 256 + wc * 64 + 16 * fq;
;         float rsv[8];
; #pragma unroll
;         for (int idx = 0; idx < 8; ++idx) rsv[idx] = ssq[row0 + (idx >> 2) * 128 + (idx & 3) * 16];
; #pragma unroll
;         for (int ai = 0; ai < 2; ++ai)
; #pragma unroll
;             for (int m = 0; m < 4; ++m) {
;                 const int row = row0 + ai * 128 + m * 16; const float rs = rsqrtf(rsv[ai * 4 + m] * (1.f / 1024.f) + EPS);
;                 u32x4 w[2];
; #pragma unroll
;                 for (int bj = 0; bj < 2; ++bj) {
;                     float v[8];
; #pragma unroll
;                     for (int n = 0; n < 2; ++n)
; #pragma unroll
;                         for (int j = 0; j < 4; ++j) { const float a = acc[ai][bj][m][n][j] * rs; v[n * 4 + j] = act ? siluf_(a) : a; }
;                     w[bj].x = pk2(v[0], v[1]); w[bj].y = pk2(v[2], v[3]); w[bj].z = pk2(v[4], v[5]); w[bj].w = pk2(v[6], v[7]);
;                 }
;                 u32x4* op = (u32x4*)(base + (size_t)row * DM + col0); op[0] = w[0]; op[1] = w[1];
.LBB0_347:
	v_lshl_add_u32 v140, s40, 8, v144
	v_ashrrev_i32_e32 v141, 31, v140
	v_lshl_add_u64 v[142:143], v[140:141], 2, s[6:7]
	s_ashr_i32 s2, s39, 2
	s_cmp_eq_u32 s2, 3
	s_cselect_b64 s[18:19], -1, 0
	s_ashr_i32 s3, s2, 31
	s_lshl_b64 s[2:3], s[2:3], 26
	s_lshl_b32 s11, s39, 8
	s_cmp_lt_u32 s39, 4
	s_cselect_b64 s[20:21], -1, 0
	s_or_b64 vcc, s[20:21], s[18:19]
	s_add_u32 s2, s31, s2
	s_addc_u32 s3, s36, s3
	s_and_b32 s11, s11, 0x300
	v_or_b32_e32 v142, s11, v146
	v_lshlrev_b32_e32 v188, 1, v142
	v_lshl_add_u64 v[142:143], s[2:3], 0, v[188:189]
	s_waitcnt vmcnt(0)
	v_mov_b32_e32 v155, v224
	v_mov_b32_e32 v154, v227
	v_mov_b32_e32 v153, v234
	v_mov_b32_e32 v152, v235
	v_mov_b32_e32 v151, v236
	v_mov_b32_e32 v150, v239
	v_mov_b32_e32 v149, v240
	v_mov_b32_e32 v148, v241
	s_and_b32 s32, s10, 0x7f
	v_lshl_add_u32 v232, s32, 8, v144
	v_ashrrev_i32_e32 v233, 31, v232
	v_lshl_add_u64 v[232:233], v[232:233], 2, s[6:7]
	global_load_dword v224, v[232:233], off
	global_load_dword v227, v[232:233], off offset:64
	global_load_dword v234, v[232:233], off offset:128
	global_load_dword v235, v[232:233], off offset:192
	global_load_dword v236, v[232:233], off offset:512
	global_load_dword v239, v[232:233], off offset:576
	global_load_dword v240, v[232:233], off offset:640
	global_load_dword v241, v[232:233], off offset:704
	v_fmamk_f32 v155, v155, 0x3a800000, v226
	v_cmp_gt_f32_e64 s[2:3], s33, v155
	v_mul_f32_e32 v156, 0x4b800000, v155
	s_nop 0
	v_cndmask_b32_e64 v155, v155, v156, s[2:3]
	v_rsq_f32_e32 v155, v155
	s_nop 0
	v_mul_f32_e32 v156, 0x45800000, v155
	v_cndmask_b32_e64 v155, v155, v156, s[2:3]
	v_mul_f32_e32 v124, v124, v155
	v_mul_f32_e32 v156, 0xbfb8aa3b, v124
	v_exp_f32_e32 v156, v156
	v_mul_f32_e32 v125, v125, v155
	v_mul_f32_e32 v126, v126, v155
	v_mul_f32_e32 v127, v127, v155
	v_add_f32_e32 v156, 1.0, v156
	v_rcp_f32_e32 v156, v156
	v_mul_f32_e32 v120, v120, v155
	v_mul_f32_e32 v116, v116, v155
	v_mul_f32_e32 v117, v117, v155
	v_mul_f32_e32 v156, v124, v156
	v_cndmask_b32_e32 v124, v124, v156, vcc
	v_mul_f32_e32 v156, 0xbfb8aa3b, v125
	v_exp_f32_e32 v156, v156
	v_mul_f32_e32 v118, v118, v155
	v_mul_f32_e32 v119, v119, v155
	v_mul_f32_e32 v112, v112, v155
	v_add_f32_e32 v156, 1.0, v156
	v_rcp_f32_e32 v156, v156
	v_mul_f32_e32 v113, v113, v155
	v_mul_f32_e32 v114, v114, v155
	v_mul_f32_e32 v156, v125, v156
	v_cndmask_b32_e32 v125, v125, v156, vcc
	v_mul_f32_e32 v156, 0xbfb8aa3b, v126
	v_exp_f32_e32 v156, v156
	s_nop 0
	v_add_f32_e32 v156, 1.0, v156
	v_rcp_f32_e32 v156, v156
	s_nop 0
	v_mul_f32_e32 v156, v126, v156
	v_cndmask_b32_e32 v126, v126, v156, vcc
	v_mul_f32_e32 v156, 0xbfb8aa3b, v127
	v_exp_f32_e32 v156, v156
	s_nop 0
	v_add_f32_e32 v156, 1.0, v156
	v_rcp_f32_e32 v156, v156
	s_nop 0
	v_mul_f32_e32 v156, v127, v156
	v_cndmask_b32_e32 v127, v127, v156, vcc
	v_mul_f32_e32 v156, 0xbfb8aa3b, v120
	v_exp_f32_e32 v156, v156
	s_nop 0
	v_add_f32_e32 v156, 1.0, v156
	v_rcp_f32_e32 v156, v156
	s_nop 0
	v_mul_f32_e32 v156, v120, v156
	v_cndmask_b32_e32 v156, v120, v156, vcc
	v_mul_f32_e32 v120, v121, v155
	v_mul_f32_e32 v121, 0xbfb8aa3b, v120
	v_exp_f32_e32 v121, v121
	s_nop 0
	v_add_f32_e32 v121, 1.0, v121
	v_rcp_f32_e32 v121, v121
	s_nop 0
	v_mul_f32_e32 v121, v120, v121
	v_cndmask_b32_e32 v157, v120, v121, vcc
	v_mul_f32_e32 v120, v122, v155
	v_mul_f32_e32 v121, 0xbfb8aa3b, v120
	v_exp_f32_e32 v121, v121
	v_cvt_pk_bf16_f32 v122, v156, v157
	v_add_f32_e32 v121, 1.0, v121
	v_rcp_f32_e32 v121, v121
	s_nop 0
	v_mul_f32_e32 v121, v120, v121
	v_cndmask_b32_e32 v158, v120, v121, vcc
	v_mul_f32_e32 v120, v123, v155
	v_mul_f32_e32 v121, 0xbfb8aa3b, v120
	v_exp_f32_e32 v121, v121
	s_nop 0
	v_add_f32_e32 v121, 1.0, v121
	v_rcp_f32_e32 v121, v121
	s_nop 0
	v_mul_f32_e32 v121, v120, v121
	v_cndmask_b32_e32 v123, v120, v121, vcc
	v_cvt_pk_bf16_f32 v120, v124, v125
	v_mul_f32_e32 v124, 0xbfb8aa3b, v116
	v_exp_f32_e32 v124, v124
	v_cvt_pk_bf16_f32 v121, v126, v127
	v_cvt_pk_bf16_f32 v123, v158, v123
	v_add_f32_e32 v124, 1.0, v124
	v_rcp_f32_e32 v124, v124
	s_nop 0
	v_mul_f32_e32 v124, v116, v124
	v_cndmask_b32_e32 v116, v116, v124, vcc
	v_mul_f32_e32 v124, 0xbfb8aa3b, v117
	v_exp_f32_e32 v124, v124
	s_nop 0
	v_add_f32_e32 v124, 1.0, v124
	v_rcp_f32_e32 v124, v124
	s_nop 0
	v_mul_f32_e32 v124, v117, v124
	v_cndmask_b32_e32 v117, v117, v124, vcc
	v_mul_f32_e32 v124, 0xbfb8aa3b, v118
	v_exp_f32_e32 v124, v124
	s_nop 0
	v_add_f32_e32 v124, 1.0, v124
	v_rcp_f32_e32 v124, v124
	s_nop 0
	v_mul_f32_e32 v124, v118, v124
	v_cndmask_b32_e32 v118, v118, v124, vcc
	v_mul_f32_e32 v124, 0xbfb8aa3b, v119
	v_exp_f32_e32 v124, v124
	s_nop 0
	v_add_f32_e32 v124, 1.0, v124
	v_rcp_f32_e32 v124, v124
	s_nop 0
	v_mul_f32_e32 v124, v119, v124
	v_cndmask_b32_e32 v119, v119, v124, vcc
	v_mul_f32_e32 v124, 0xbfb8aa3b, v112
	v_exp_f32_e32 v124, v124
	s_nop 0
	v_add_f32_e32 v124, 1.0, v124
	v_rcp_f32_e32 v124, v124
	s_nop 0
	v_mul_f32_e32 v124, v112, v124
	v_cndmask_b32_e32 v112, v112, v124, vcc
	v_mul_f32_e32 v124, 0xbfb8aa3b, v113
	v_exp_f32_e32 v124, v124
	s_nop 0
	v_add_f32_e32 v124, 1.0, v124
	v_rcp_f32_e32 v124, v124
	s_nop 0
	v_mul_f32_e32 v124, v113, v124
	v_cndmask_b32_e32 v113, v113, v124, vcc
	v_mul_f32_e32 v124, 0xbfb8aa3b, v114
	v_exp_f32_e32 v124, v124
	s_nop 0
	v_add_f32_e32 v124, 1.0, v124
	v_rcp_f32_e32 v124, v124
	s_nop 0
	v_mul_f32_e32 v124, v114, v124
	v_cndmask_b32_e32 v124, v114, v124, vcc
	v_mul_f32_e32 v114, v115, v155
	v_mul_f32_e32 v115, 0xbfb8aa3b, v114
	v_exp_f32_e32 v115, v115
	s_nop 0
	v_add_f32_e32 v115, 1.0, v115
	v_rcp_f32_e32 v115, v115
	s_nop 0
	v_mul_f32_e32 v115, v114, v115
	v_cndmask_b32_e32 v125, v114, v115, vcc
	v_cvt_pk_bf16_f32 v114, v116, v117
; __device__ __forceinline__ unsigned pk2(float lo, float hi) { f32x2 v = {lo, hi}; bf2_t b = __builtin_convertvector(v, bf2_t); return __builtin_bit_cast(unsigned, b); }
; __device__ __forceinline__ float siluf_(float x) { return x * sigmoidf_(x); }
;     __device__ __forceinline__ void operator()(const AccT& acc, const Unit& u, int wr, int wc, int fr, int fq) const {
;     ...
;         for (int ai = 0; ai < 2; ++ai)
; #pragma unroll
;             for (int m = 0; m < 4; ++m) {
;                 const int row = row0 + ai * 128 + m * 16; const float rs = rsqrtf(rsv[ai * 4 + m] * (1.f / 1024.f) + EPS);
;                 u32x4 w[2];
; #pragma unroll
;                 for (int bj = 0; bj < 2; ++bj) {
;                     float v[8];
; #pragma unroll
;                     for (int n = 0; n < 2; ++n)
; #pragma unroll
;                         for (int j = 0; j < 4; ++j) { const float a = acc[ai][bj][m][n][j] * rs; v[n * 4 + j] = act ? siluf_(a) : a; }
;                     w[bj].x = pk2(v[0], v[1]); w[bj].y = pk2(v[2], v[3]); w[bj].z = pk2(v[4], v[5]); w[bj].w = pk2(v[6], v[7]);
;                 }
;                 u32x4* op = (u32x4*)(base + (size_t)row * DM + col0); op[0] = w[0]; op[1] = w[1];
	v_cvt_pk_bf16_f32 v116, v112, v113
	v_lshlrev_b64 v[112:113], 11, v[140:141]
	v_lshl_add_u64 v[112:113], v[142:143], 0, v[112:113]
	v_cvt_pk_bf16_f32 v115, v118, v119
	v_cvt_pk_bf16_f32 v117, v124, v125
	global_store_dwordx4 v[112:113], v[120:123], off
	global_store_dwordx4 v[112:113], v[114:117], off offset:16
	s_nop 1
	v_fmamk_f32 v114, v154, 0x3a800000, v226
	v_cmp_gt_f32_e64 s[2:3], s33, v114
	v_mul_f32_e32 v115, 0x4b800000, v114
	s_nop 0
	v_cndmask_b32_e64 v114, v114, v115, s[2:3]
	v_rsq_f32_e32 v114, v114
	s_nop 0
	v_mul_f32_e32 v115, 0x45800000, v114
	v_cndmask_b32_e64 v114, v114, v115, s[2:3]
	v_mul_f32_e32 v108, v108, v114
	v_mul_f32_e32 v115, 0xbfb8aa3b, v108
	v_exp_f32_e32 v115, v115
	v_mul_f32_e32 v109, v109, v114
	v_mul_f32_e32 v110, v110, v114
	v_mul_f32_e32 v111, v111, v114
	v_add_f32_e32 v115, 1.0, v115
	v_rcp_f32_e32 v115, v115
	v_mul_f32_e32 v104, v104, v114
	v_mul_f32_e32 v100, v100, v114
	v_mul_f32_e32 v101, v101, v114
	v_mul_f32_e32 v115, v108, v115
	v_cndmask_b32_e32 v108, v108, v115, vcc
	v_mul_f32_e32 v115, 0xbfb8aa3b, v109
	v_exp_f32_e32 v115, v115
	v_mul_f32_e32 v102, v102, v114
	v_mul_f32_e32 v103, v103, v114
	v_mul_f32_e32 v96, v96, v114
	v_add_f32_e32 v115, 1.0, v115
	v_rcp_f32_e32 v115, v115
	s_nop 0
	v_mul_f32_e32 v115, v109, v115
	v_cndmask_b32_e32 v109, v109, v115, vcc
	v_mul_f32_e32 v115, 0xbfb8aa3b, v110
	v_exp_f32_e32 v115, v115
	s_nop 0
	v_add_f32_e32 v115, 1.0, v115
	v_rcp_f32_e32 v115, v115
	s_nop 0
	v_mul_f32_e32 v115, v110, v115
	v_cndmask_b32_e32 v110, v110, v115, vcc
	v_mul_f32_e32 v115, 0xbfb8aa3b, v111
	v_exp_f32_e32 v115, v115
	s_nop 0
	v_add_f32_e32 v115, 1.0, v115
	v_rcp_f32_e32 v115, v115
	s_nop 0
	v_mul_f32_e32 v115, v111, v115
	v_cndmask_b32_e32 v111, v111, v115, vcc
	v_mul_f32_e32 v115, 0xbfb8aa3b, v104
	v_exp_f32_e32 v115, v115
	s_nop 0
	v_add_f32_e32 v115, 1.0, v115
	v_rcp_f32_e32 v115, v115
	s_nop 0
	v_mul_f32_e32 v115, v104, v115
	v_cndmask_b32_e32 v115, v104, v115, vcc
	v_mul_f32_e32 v104, v105, v114
	v_mul_f32_e32 v105, 0xbfb8aa3b, v104
	v_exp_f32_e32 v105, v105
	s_nop 0
	v_add_f32_e32 v105, 1.0, v105
	v_rcp_f32_e32 v105, v105
	s_nop 0
	v_mul_f32_e32 v105, v104, v105
	v_cndmask_b32_e32 v116, v104, v105, vcc
	v_mul_f32_e32 v104, v106, v114
	v_mul_f32_e32 v105, 0xbfb8aa3b, v104
	v_exp_f32_e32 v105, v105
	v_cvt_pk_bf16_f32 v106, v115, v116
	v_add_f32_e32 v105, 1.0, v105
	v_rcp_f32_e32 v105, v105
	s_nop 0
	v_mul_f32_e32 v105, v104, v105
	v_cndmask_b32_e32 v117, v104, v105, vcc
	v_mul_f32_e32 v104, v107, v114
	v_mul_f32_e32 v105, 0xbfb8aa3b, v104
	v_exp_f32_e32 v105, v105
	s_nop 0
	v_add_f32_e32 v105, 1.0, v105
	v_rcp_f32_e32 v105, v105
	s_nop 0
	v_mul_f32_e32 v105, v104, v105
	v_cndmask_b32_e32 v107, v104, v105, vcc
	v_cvt_pk_bf16_f32 v104, v108, v109
	v_mul_f32_e32 v108, 0xbfb8aa3b, v100
	v_exp_f32_e32 v108, v108
	v_cvt_pk_bf16_f32 v105, v110, v111
	v_cvt_pk_bf16_f32 v107, v117, v107
	v_add_f32_e32 v108, 1.0, v108
	v_rcp_f32_e32 v108, v108
	s_nop 0
	v_mul_f32_e32 v108, v100, v108
	v_cndmask_b32_e32 v100, v100, v108, vcc
	v_mul_f32_e32 v108, 0xbfb8aa3b, v101
	v_exp_f32_e32 v108, v108
	s_nop 0
	v_add_f32_e32 v108, 1.0, v108
	v_rcp_f32_e32 v108, v108
	s_nop 0
	v_mul_f32_e32 v108, v101, v108
	v_cndmask_b32_e32 v101, v101, v108, vcc
	v_mul_f32_e32 v108, 0xbfb8aa3b, v102
	v_exp_f32_e32 v108, v108
	s_nop 0
	v_add_f32_e32 v108, 1.0, v108
	v_rcp_f32_e32 v108, v108
	s_nop 0
	v_mul_f32_e32 v108, v102, v108
	v_cndmask_b32_e32 v102, v102, v108, vcc
	v_mul_f32_e32 v108, 0xbfb8aa3b, v103
	v_exp_f32_e32 v108, v108
	s_nop 0
	v_add_f32_e32 v108, 1.0, v108
	v_rcp_f32_e32 v108, v108
	s_nop 0
	v_mul_f32_e32 v108, v103, v108
	v_cndmask_b32_e32 v103, v103, v108, vcc
	v_mul_f32_e32 v108, 0xbfb8aa3b, v96
	v_exp_f32_e32 v108, v108
	s_nop 0
	v_add_f32_e32 v108, 1.0, v108
	v_rcp_f32_e32 v108, v108
	s_nop 0
	v_mul_f32_e32 v108, v96, v108
	v_cndmask_b32_e32 v108, v96, v108, vcc
	v_mul_f32_e32 v96, v97, v114
	v_mul_f32_e32 v97, 0xbfb8aa3b, v96
	v_exp_f32_e32 v97, v97
	s_nop 0
	v_add_f32_e32 v97, 1.0, v97
	v_rcp_f32_e32 v97, v97
	s_nop 0
	v_mul_f32_e32 v97, v96, v97
	v_cndmask_b32_e32 v109, v96, v97, vcc
	v_mul_f32_e32 v96, v98, v114
	v_mul_f32_e32 v97, 0xbfb8aa3b, v96
	v_exp_f32_e32 v97, v97
	v_cvt_pk_bf16_f32 v98, v108, v109
	v_add_f32_e32 v97, 1.0, v97
	v_rcp_f32_e32 v97, v97
	s_nop 0
	v_mul_f32_e32 v97, v96, v97
	v_cndmask_b32_e32 v110, v96, v97, vcc
	v_mul_f32_e32 v96, v99, v114
	v_mul_f32_e32 v97, 0xbfb8aa3b, v96
	v_exp_f32_e32 v97, v97
	s_nop 0
	v_add_f32_e32 v97, 1.0, v97
	v_rcp_f32_e32 v97, v97
	s_nop 0
	v_mul_f32_e32 v97, v96, v97
	v_cndmask_b32_e32 v99, v96, v97, vcc
	v_cvt_pk_bf16_f32 v96, v100, v101
	v_or_b32_e32 v100, 16, v140
	v_ashrrev_i32_e32 v101, 31, v100
	v_lshlrev_b64 v[100:101], 11, v[100:101]
	v_lshl_add_u64 v[100:101], v[142:143], 0, v[100:101]
	v_cvt_pk_bf16_f32 v97, v102, v103
	v_cvt_pk_bf16_f32 v99, v110, v99
	global_store_dwordx4 v[100:101], v[104:107], off
	global_store_dwordx4 v[100:101], v[96:99], off offset:16
	s_nop 1
	v_fmamk_f32 v96, v153, 0x3a800000, v226
	v_cmp_gt_f32_e64 s[2:3], s33, v96
	v_mul_f32_e32 v97, 0x4b800000, v96
	s_nop 0
	v_cndmask_b32_e64 v96, v96, v97, s[2:3]
	v_rsq_f32_e32 v96, v96
	s_nop 0
	v_mul_f32_e32 v97, 0x45800000, v96
	v_cndmask_b32_e64 v96, v96, v97, s[2:3]
	v_mul_f32_e32 v92, v92, v96
	v_mul_f32_e32 v97, 0xbfb8aa3b, v92
	v_exp_f32_e32 v97, v97
	v_mul_f32_e32 v93, v93, v96
	v_mul_f32_e32 v94, v94, v96
	v_mul_f32_e32 v95, v95, v96
	v_add_f32_e32 v97, 1.0, v97
	v_rcp_f32_e32 v97, v97
	v_mul_f32_e32 v88, v88, v96
	v_mul_f32_e32 v84, v84, v96
	v_mul_f32_e32 v85, v85, v96
	v_mul_f32_e32 v97, v92, v97
	v_cndmask_b32_e32 v92, v92, v97, vcc
; __device__ __forceinline__ unsigned pk2(float lo, float hi) { f32x2 v = {lo, hi}; bf2_t b = __builtin_convertvector(v, bf2_t); return __builtin_bit_cast(unsigned, b); }
; __device__ __forceinline__ float siluf_(float x) { return x * sigmoidf_(x); }
;     __device__ __forceinline__ void operator()(const AccT& acc, const Unit& u, int wr, int wc, int fr, int fq) const {
;     ...
;         for (int ai = 0; ai < 2; ++ai)
; #pragma unroll
;             for (int m = 0; m < 4; ++m) {
;                 const int row = row0 + ai * 128 + m * 16; const float rs = rsqrtf(rsv[ai * 4 + m] * (1.f / 1024.f) + EPS);
;                 u32x4 w[2];
; #pragma unroll
;                 for (int bj = 0; bj < 2; ++bj) {
;                     float v[8];
; #pragma unroll
;                     for (int n = 0; n < 2; ++n)
; #pragma unroll
;                         for (int j = 0; j < 4; ++j) { const float a = acc[ai][bj][m][n][j] * rs; v[n * 4 + j] = act ? siluf_(a) : a; }
;                     w[bj].x = pk2(v[0], v[1]); w[bj].y = pk2(v[2], v[3]); w[bj].z = pk2(v[4], v[5]); w[bj].w = pk2(v[6], v[7]);
;                 }
;                 u32x4* op = (u32x4*)(base + (size_t)row * DM + col0); op[0] = w[0]; op[1] = w[1];
	v_mul_f32_e32 v97, 0xbfb8aa3b, v93
	v_exp_f32_e32 v97, v97
	v_mul_f32_e32 v86, v86, v96
	v_mul_f32_e32 v87, v87, v96
	v_mul_f32_e32 v80, v80, v96
	v_add_f32_e32 v97, 1.0, v97
	v_rcp_f32_e32 v97, v97
	s_nop 0
	v_mul_f32_e32 v97, v93, v97
	v_cndmask_b32_e32 v93, v93, v97, vcc
	v_mul_f32_e32 v97, 0xbfb8aa3b, v94
	v_exp_f32_e32 v97, v97
	s_nop 0
	v_add_f32_e32 v97, 1.0, v97
	v_rcp_f32_e32 v97, v97
	s_nop 0
	v_mul_f32_e32 v97, v94, v97
	v_cndmask_b32_e32 v94, v94, v97, vcc
	v_mul_f32_e32 v97, 0xbfb8aa3b, v95
	v_exp_f32_e32 v97, v97
	s_nop 0
	v_add_f32_e32 v97, 1.0, v97
	v_rcp_f32_e32 v97, v97
	s_nop 0
	v_mul_f32_e32 v97, v95, v97
	v_cndmask_b32_e32 v95, v95, v97, vcc
	v_mul_f32_e32 v97, 0xbfb8aa3b, v88
	v_exp_f32_e32 v97, v97
	s_nop 0
	v_add_f32_e32 v97, 1.0, v97
	v_rcp_f32_e32 v97, v97
	s_nop 0
	v_mul_f32_e32 v97, v88, v97
	v_cndmask_b32_e32 v97, v88, v97, vcc
	v_mul_f32_e32 v88, v89, v96
	v_mul_f32_e32 v89, 0xbfb8aa3b, v88
	v_exp_f32_e32 v89, v89
	s_nop 0
	v_add_f32_e32 v89, 1.0, v89
	v_rcp_f32_e32 v89, v89
	s_nop 0
	v_mul_f32_e32 v89, v88, v89
	v_cndmask_b32_e32 v98, v88, v89, vcc
	v_mul_f32_e32 v88, v90, v96
	v_mul_f32_e32 v89, 0xbfb8aa3b, v88
	v_exp_f32_e32 v89, v89
	v_cvt_pk_bf16_f32 v90, v97, v98
	v_add_f32_e32 v89, 1.0, v89
	v_rcp_f32_e32 v89, v89
	s_nop 0
	v_mul_f32_e32 v89, v88, v89
	v_cndmask_b32_e32 v99, v88, v89, vcc
	v_mul_f32_e32 v88, v91, v96
	v_mul_f32_e32 v89, 0xbfb8aa3b, v88
	v_exp_f32_e32 v89, v89
	s_nop 0
	v_add_f32_e32 v89, 1.0, v89
	v_rcp_f32_e32 v89, v89
	s_nop 0
	v_mul_f32_e32 v89, v88, v89
	v_cndmask_b32_e32 v91, v88, v89, vcc
	v_cvt_pk_bf16_f32 v88, v92, v93
	v_mul_f32_e32 v92, 0xbfb8aa3b, v84
	v_exp_f32_e32 v92, v92
	v_cvt_pk_bf16_f32 v89, v94, v95
	v_cvt_pk_bf16_f32 v91, v99, v91
	v_add_f32_e32 v92, 1.0, v92
	v_rcp_f32_e32 v92, v92
	s_nop 0
	v_mul_f32_e32 v92, v84, v92
	v_cndmask_b32_e32 v84, v84, v92, vcc
	v_mul_f32_e32 v92, 0xbfb8aa3b, v85
	v_exp_f32_e32 v92, v92
	s_nop 0
	v_add_f32_e32 v92, 1.0, v92
	v_rcp_f32_e32 v92, v92
	s_nop 0
	v_mul_f32_e32 v92, v85, v92
	v_cndmask_b32_e32 v85, v85, v92, vcc
	v_mul_f32_e32 v92, 0xbfb8aa3b, v86
	v_exp_f32_e32 v92, v92
	s_nop 0
	v_add_f32_e32 v92, 1.0, v92
	v_rcp_f32_e32 v92, v92
	s_nop 0
	v_mul_f32_e32 v92, v86, v92
	v_cndmask_b32_e32 v86, v86, v92, vcc
	v_mul_f32_e32 v92, 0xbfb8aa3b, v87
	v_exp_f32_e32 v92, v92
	s_nop 0
	v_add_f32_e32 v92, 1.0, v92
	v_rcp_f32_e32 v92, v92
	s_nop 0
	v_mul_f32_e32 v92, v87, v92
	v_cndmask_b32_e32 v87, v87, v92, vcc
	v_mul_f32_e32 v92, 0xbfb8aa3b, v80
	v_exp_f32_e32 v92, v92
	s_nop 0
	v_add_f32_e32 v92, 1.0, v92
	v_rcp_f32_e32 v92, v92
	s_nop 0
	v_mul_f32_e32 v92, v80, v92
	v_cndmask_b32_e32 v92, v80, v92, vcc
	v_mul_f32_e32 v80, v81, v96
	v_mul_f32_e32 v81, 0xbfb8aa3b, v80
	v_exp_f32_e32 v81, v81
	s_nop 0
	v_add_f32_e32 v81, 1.0, v81
	v_rcp_f32_e32 v81, v81
	s_nop 0
	v_mul_f32_e32 v81, v80, v81
	v_cndmask_b32_e32 v93, v80, v81, vcc
	v_mul_f32_e32 v80, v82, v96
	v_mul_f32_e32 v81, 0xbfb8aa3b, v80
	v_exp_f32_e32 v81, v81
	v_cvt_pk_bf16_f32 v82, v92, v93
	v_add_f32_e32 v81, 1.0, v81
	v_rcp_f32_e32 v81, v81
	s_nop 0
	v_mul_f32_e32 v81, v80, v81
	v_cndmask_b32_e32 v94, v80, v81, vcc
	v_mul_f32_e32 v80, v83, v96
	v_mul_f32_e32 v81, 0xbfb8aa3b, v80
	v_exp_f32_e32 v81, v81
	s_nop 0
	v_add_f32_e32 v81, 1.0, v81
	v_rcp_f32_e32 v81, v81
	s_nop 0
	v_mul_f32_e32 v81, v80, v81
	v_cndmask_b32_e32 v83, v80, v81, vcc
	v_cvt_pk_bf16_f32 v80, v84, v85
	v_or_b32_e32 v84, 32, v140
	v_ashrrev_i32_e32 v85, 31, v84
	v_lshlrev_b64 v[84:85], 11, v[84:85]
	v_lshl_add_u64 v[84:85], v[142:143], 0, v[84:85]
	v_cvt_pk_bf16_f32 v81, v86, v87
	v_cvt_pk_bf16_f32 v83, v94, v83
	global_store_dwordx4 v[84:85], v[88:91], off
	global_store_dwordx4 v[84:85], v[80:83], off offset:16
	s_nop 1
	v_fmamk_f32 v80, v152, 0x3a800000, v226
	v_cmp_gt_f32_e64 s[2:3], s33, v80
	v_mul_f32_e32 v81, 0x4b800000, v80
	s_nop 0
	v_cndmask_b32_e64 v80, v80, v81, s[2:3]
	v_rsq_f32_e32 v80, v80
	s_nop 0
	v_mul_f32_e32 v81, 0x45800000, v80
	v_cndmask_b32_e64 v80, v80, v81, s[2:3]
	v_mul_f32_e32 v76, v76, v80
	v_mul_f32_e32 v81, 0xbfb8aa3b, v76
	v_exp_f32_e32 v81, v81
	v_mul_f32_e32 v77, v77, v80
	v_mul_f32_e32 v78, v78, v80
	v_mul_f32_e32 v79, v79, v80
	v_add_f32_e32 v81, 1.0, v81
	v_rcp_f32_e32 v81, v81
	v_mul_f32_e32 v72, v72, v80
	v_mul_f32_e32 v68, v68, v80
	v_mul_f32_e32 v69, v69, v80
	v_mul_f32_e32 v81, v76, v81
	v_cndmask_b32_e32 v76, v76, v81, vcc
	v_mul_f32_e32 v81, 0xbfb8aa3b, v77
	v_exp_f32_e32 v81, v81
	v_mul_f32_e32 v70, v70, v80
	v_mul_f32_e32 v71, v71, v80
	v_mul_f32_e32 v64, v64, v80
	v_add_f32_e32 v81, 1.0, v81
	v_rcp_f32_e32 v81, v81
	s_nop 0
	v_mul_f32_e32 v81, v77, v81
	v_cndmask_b32_e32 v77, v77, v81, vcc
	v_mul_f32_e32 v81, 0xbfb8aa3b, v78
	v_exp_f32_e32 v81, v81
	s_nop 0
	v_add_f32_e32 v81, 1.0, v81
	v_rcp_f32_e32 v81, v81
	s_nop 0
	v_mul_f32_e32 v81, v78, v81
	v_cndmask_b32_e32 v78, v78, v81, vcc
	v_mul_f32_e32 v81, 0xbfb8aa3b, v79
	v_exp_f32_e32 v81, v81
	s_nop 0
	v_add_f32_e32 v81, 1.0, v81
	v_rcp_f32_e32 v81, v81
	s_nop 0
	v_mul_f32_e32 v81, v79, v81
	v_cndmask_b32_e32 v79, v79, v81, vcc
	v_mul_f32_e32 v81, 0xbfb8aa3b, v72
	v_exp_f32_e32 v81, v81
	s_nop 0
	v_add_f32_e32 v81, 1.0, v81
	v_rcp_f32_e32 v81, v81
	s_nop 0
	v_mul_f32_e32 v81, v72, v81
	v_cndmask_b32_e32 v81, v72, v81, vcc
	v_mul_f32_e32 v72, v73, v80
	v_mul_f32_e32 v73, 0xbfb8aa3b, v72
	v_exp_f32_e32 v73, v73
	s_nop 0
	v_add_f32_e32 v73, 1.0, v73
	v_rcp_f32_e32 v73, v73
	s_nop 0
	v_mul_f32_e32 v73, v72, v73
	v_cndmask_b32_e32 v82, v72, v73, vcc
	v_mul_f32_e32 v72, v74, v80
	v_mul_f32_e32 v73, 0xbfb8aa3b, v72
	v_exp_f32_e32 v73, v73
	v_cvt_pk_bf16_f32 v74, v81, v82
	v_add_f32_e32 v73, 1.0, v73
	v_rcp_f32_e32 v73, v73
; __device__ __forceinline__ unsigned pk2(float lo, float hi) { f32x2 v = {lo, hi}; bf2_t b = __builtin_convertvector(v, bf2_t); return __builtin_bit_cast(unsigned, b); }
; __device__ __forceinline__ float siluf_(float x) { return x * sigmoidf_(x); }
;     __device__ __forceinline__ void operator()(const AccT& acc, const Unit& u, int wr, int wc, int fr, int fq) const {
;     ...
;         for (int ai = 0; ai < 2; ++ai)
; #pragma unroll
;             for (int m = 0; m < 4; ++m) {
;                 const int row = row0 + ai * 128 + m * 16; const float rs = rsqrtf(rsv[ai * 4 + m] * (1.f / 1024.f) + EPS);
;                 u32x4 w[2];
; #pragma unroll
;                 for (int bj = 0; bj < 2; ++bj) {
;                     float v[8];
; #pragma unroll
;                     for (int n = 0; n < 2; ++n)
; #pragma unroll
;                         for (int j = 0; j < 4; ++j) { const float a = acc[ai][bj][m][n][j] * rs; v[n * 4 + j] = act ? siluf_(a) : a; }
;                     w[bj].x = pk2(v[0], v[1]); w[bj].y = pk2(v[2], v[3]); w[bj].z = pk2(v[4], v[5]); w[bj].w = pk2(v[6], v[7]);
;                 }
;                 u32x4* op = (u32x4*)(base + (size_t)row * DM + col0); op[0] = w[0]; op[1] = w[1];
	s_nop 0
	v_mul_f32_e32 v73, v72, v73
	v_cndmask_b32_e32 v83, v72, v73, vcc
	v_mul_f32_e32 v72, v75, v80
	v_mul_f32_e32 v73, 0xbfb8aa3b, v72
	v_exp_f32_e32 v73, v73
	s_nop 0
	v_add_f32_e32 v73, 1.0, v73
	v_rcp_f32_e32 v73, v73
	s_nop 0
	v_mul_f32_e32 v73, v72, v73
	v_cndmask_b32_e32 v75, v72, v73, vcc
	v_cvt_pk_bf16_f32 v72, v76, v77
	v_mul_f32_e32 v76, 0xbfb8aa3b, v68
	v_exp_f32_e32 v76, v76
	v_cvt_pk_bf16_f32 v73, v78, v79
	v_cvt_pk_bf16_f32 v75, v83, v75
	v_add_f32_e32 v76, 1.0, v76
	v_rcp_f32_e32 v76, v76
	s_nop 0
	v_mul_f32_e32 v76, v68, v76
	v_cndmask_b32_e32 v68, v68, v76, vcc
	v_mul_f32_e32 v76, 0xbfb8aa3b, v69
	v_exp_f32_e32 v76, v76
	s_nop 0
	v_add_f32_e32 v76, 1.0, v76
	v_rcp_f32_e32 v76, v76
	s_nop 0
	v_mul_f32_e32 v76, v69, v76
	v_cndmask_b32_e32 v69, v69, v76, vcc
	v_mul_f32_e32 v76, 0xbfb8aa3b, v70
	v_exp_f32_e32 v76, v76
	s_nop 0
	v_add_f32_e32 v76, 1.0, v76
	v_rcp_f32_e32 v76, v76
	s_nop 0
	v_mul_f32_e32 v76, v70, v76
	v_cndmask_b32_e32 v70, v70, v76, vcc
	v_mul_f32_e32 v76, 0xbfb8aa3b, v71
	v_exp_f32_e32 v76, v76
	s_nop 0
	v_add_f32_e32 v76, 1.0, v76
	v_rcp_f32_e32 v76, v76
	s_nop 0
	v_mul_f32_e32 v76, v71, v76
	v_cndmask_b32_e32 v71, v71, v76, vcc
	v_mul_f32_e32 v76, 0xbfb8aa3b, v64
	v_exp_f32_e32 v76, v76
	s_nop 0
	v_add_f32_e32 v76, 1.0, v76
	v_rcp_f32_e32 v76, v76
	s_nop 0
	v_mul_f32_e32 v76, v64, v76
	v_cndmask_b32_e32 v76, v64, v76, vcc
	v_mul_f32_e32 v64, v65, v80
	v_mul_f32_e32 v65, 0xbfb8aa3b, v64
	v_exp_f32_e32 v65, v65
	s_nop 0
	v_add_f32_e32 v65, 1.0, v65
	v_rcp_f32_e32 v65, v65
	s_nop 0
	v_mul_f32_e32 v65, v64, v65
	v_cndmask_b32_e32 v77, v64, v65, vcc
	v_mul_f32_e32 v64, v66, v80
	v_mul_f32_e32 v65, 0xbfb8aa3b, v64
	v_exp_f32_e32 v65, v65
	v_cvt_pk_bf16_f32 v66, v76, v77
	v_add_f32_e32 v65, 1.0, v65
	v_rcp_f32_e32 v65, v65
	s_nop 0
	v_mul_f32_e32 v65, v64, v65
	v_cndmask_b32_e32 v78, v64, v65, vcc
	v_mul_f32_e32 v64, v67, v80
	v_mul_f32_e32 v65, 0xbfb8aa3b, v64
	v_exp_f32_e32 v65, v65
	s_nop 0
	v_add_f32_e32 v65, 1.0, v65
	v_rcp_f32_e32 v65, v65
	s_nop 0
	v_mul_f32_e32 v65, v64, v65
	v_cndmask_b32_e32 v67, v64, v65, vcc
	v_cvt_pk_bf16_f32 v64, v68, v69
	v_or_b32_e32 v68, 48, v140
	v_ashrrev_i32_e32 v69, 31, v68
	v_lshlrev_b64 v[68:69], 11, v[68:69]
	v_lshl_add_u64 v[68:69], v[142:143], 0, v[68:69]
	v_cvt_pk_bf16_f32 v65, v70, v71
	v_cvt_pk_bf16_f32 v67, v78, v67
	global_store_dwordx4 v[68:69], v[72:75], off
	global_store_dwordx4 v[68:69], v[64:67], off offset:16
	s_nop 1
	v_fmamk_f32 v64, v151, 0x3a800000, v226
	v_cmp_gt_f32_e64 s[2:3], s33, v64
	v_mul_f32_e32 v65, 0x4b800000, v64
	s_nop 0
	v_cndmask_b32_e64 v64, v64, v65, s[2:3]
	v_rsq_f32_e32 v64, v64
	s_nop 0
	v_mul_f32_e32 v65, 0x45800000, v64
	v_cndmask_b32_e64 v64, v64, v65, s[2:3]
	v_mul_f32_e32 v60, v60, v64
	v_mul_f32_e32 v65, 0xbfb8aa3b, v60
	v_exp_f32_e32 v65, v65
	v_mul_f32_e32 v61, v61, v64
	v_mul_f32_e32 v62, v62, v64
	v_mul_f32_e32 v63, v63, v64
	v_add_f32_e32 v65, 1.0, v65
	v_rcp_f32_e32 v65, v65
	v_mul_f32_e32 v56, v56, v64
	v_mul_f32_e32 v52, v52, v64
	v_mul_f32_e32 v53, v53, v64
	v_mul_f32_e32 v65, v60, v65
	v_cndmask_b32_e32 v60, v60, v65, vcc
	v_mul_f32_e32 v65, 0xbfb8aa3b, v61
	v_exp_f32_e32 v65, v65
	v_mul_f32_e32 v54, v54, v64
	v_mul_f32_e32 v55, v55, v64
	v_mul_f32_e32 v48, v48, v64
	v_add_f32_e32 v65, 1.0, v65
	v_rcp_f32_e32 v65, v65
	s_mov_b64 s[2:3], 0x40000
	v_mul_f32_e32 v65, v61, v65
	v_cndmask_b32_e32 v61, v61, v65, vcc
	v_mul_f32_e32 v65, 0xbfb8aa3b, v62
	v_exp_f32_e32 v65, v65
	s_nop 0
	v_add_f32_e32 v65, 1.0, v65
	v_rcp_f32_e32 v65, v65
	s_nop 0
	v_mul_f32_e32 v65, v62, v65
	v_cndmask_b32_e32 v62, v62, v65, vcc
	v_mul_f32_e32 v65, 0xbfb8aa3b, v63
	v_exp_f32_e32 v65, v65
	s_nop 0
	v_add_f32_e32 v65, 1.0, v65
	v_rcp_f32_e32 v65, v65
	s_nop 0
	v_mul_f32_e32 v65, v63, v65
	v_cndmask_b32_e32 v63, v63, v65, vcc
	v_mul_f32_e32 v65, 0xbfb8aa3b, v56
	v_exp_f32_e32 v65, v65
	s_nop 0
	v_add_f32_e32 v65, 1.0, v65
	v_rcp_f32_e32 v65, v65
	s_nop 0
	v_mul_f32_e32 v65, v56, v65
	v_cndmask_b32_e32 v65, v56, v65, vcc
	v_mul_f32_e32 v56, v57, v64
	v_mul_f32_e32 v57, 0xbfb8aa3b, v56
	v_exp_f32_e32 v57, v57
	s_nop 0
	v_add_f32_e32 v57, 1.0, v57
	v_rcp_f32_e32 v57, v57
	s_nop 0
	v_mul_f32_e32 v57, v56, v57
	v_cndmask_b32_e32 v66, v56, v57, vcc
	v_mul_f32_e32 v56, v58, v64
	v_mul_f32_e32 v57, 0xbfb8aa3b, v56
	v_exp_f32_e32 v57, v57
	v_cvt_pk_bf16_f32 v58, v65, v66
	v_add_f32_e32 v57, 1.0, v57
	v_rcp_f32_e32 v57, v57
	s_nop 0
	v_mul_f32_e32 v57, v56, v57
	v_cndmask_b32_e32 v67, v56, v57, vcc
	v_mul_f32_e32 v56, v59, v64
	v_mul_f32_e32 v57, 0xbfb8aa3b, v56
	v_exp_f32_e32 v57, v57
	s_nop 0
	v_add_f32_e32 v57, 1.0, v57
	v_rcp_f32_e32 v57, v57
	s_nop 0
	v_mul_f32_e32 v57, v56, v57
	v_cndmask_b32_e32 v59, v56, v57, vcc
	v_cvt_pk_bf16_f32 v56, v60, v61
	v_mul_f32_e32 v60, 0xbfb8aa3b, v52
	v_exp_f32_e32 v60, v60
	v_cvt_pk_bf16_f32 v57, v62, v63
	v_cvt_pk_bf16_f32 v59, v67, v59
	v_add_f32_e32 v60, 1.0, v60
	v_rcp_f32_e32 v60, v60
	s_nop 0
	v_mul_f32_e32 v60, v52, v60
	v_cndmask_b32_e32 v52, v52, v60, vcc
	v_mul_f32_e32 v60, 0xbfb8aa3b, v53
	v_exp_f32_e32 v60, v60
	s_nop 0
	v_add_f32_e32 v60, 1.0, v60
	v_rcp_f32_e32 v60, v60
	s_nop 0
	v_mul_f32_e32 v60, v53, v60
	v_cndmask_b32_e32 v53, v53, v60, vcc
	v_mul_f32_e32 v60, 0xbfb8aa3b, v54
	v_exp_f32_e32 v60, v60
	s_nop 0
	v_add_f32_e32 v60, 1.0, v60
	v_rcp_f32_e32 v60, v60
	s_nop 0
	v_mul_f32_e32 v60, v54, v60
	v_cndmask_b32_e32 v54, v54, v60, vcc
	v_mul_f32_e32 v60, 0xbfb8aa3b, v55
	v_exp_f32_e32 v60, v60
	s_nop 0
	v_add_f32_e32 v60, 1.0, v60
	v_rcp_f32_e32 v60, v60
	s_nop 0
	v_mul_f32_e32 v60, v55, v60
	v_cndmask_b32_e32 v55, v55, v60, vcc
	v_mul_f32_e32 v60, 0xbfb8aa3b, v48
	v_exp_f32_e32 v60, v60
; __device__ __forceinline__ unsigned pk2(float lo, float hi) { f32x2 v = {lo, hi}; bf2_t b = __builtin_convertvector(v, bf2_t); return __builtin_bit_cast(unsigned, b); }
; __device__ __forceinline__ float siluf_(float x) { return x * sigmoidf_(x); }
;     __device__ __forceinline__ void operator()(const AccT& acc, const Unit& u, int wr, int wc, int fr, int fq) const {
;     ...
;         for (int ai = 0; ai < 2; ++ai)
; #pragma unroll
;             for (int m = 0; m < 4; ++m) {
;                 const int row = row0 + ai * 128 + m * 16; const float rs = rsqrtf(rsv[ai * 4 + m] * (1.f / 1024.f) + EPS);
;                 u32x4 w[2];
; #pragma unroll
;                 for (int bj = 0; bj < 2; ++bj) {
;                     float v[8];
; #pragma unroll
;                     for (int n = 0; n < 2; ++n)
; #pragma unroll
;                         for (int j = 0; j < 4; ++j) { const float a = acc[ai][bj][m][n][j] * rs; v[n * 4 + j] = act ? siluf_(a) : a; }
;                     w[bj].x = pk2(v[0], v[1]); w[bj].y = pk2(v[2], v[3]); w[bj].z = pk2(v[4], v[5]); w[bj].w = pk2(v[6], v[7]);
;                 }
;                 u32x4* op = (u32x4*)(base + (size_t)row * DM + col0); op[0] = w[0]; op[1] = w[1];
	s_nop 0
	v_add_f32_e32 v60, 1.0, v60
	v_rcp_f32_e32 v60, v60
	s_nop 0
	v_mul_f32_e32 v60, v48, v60
	v_cndmask_b32_e32 v60, v48, v60, vcc
	v_mul_f32_e32 v48, v49, v64
	v_mul_f32_e32 v49, 0xbfb8aa3b, v48
	v_exp_f32_e32 v49, v49
	s_nop 0
	v_add_f32_e32 v49, 1.0, v49
	v_rcp_f32_e32 v49, v49
	s_nop 0
	v_mul_f32_e32 v49, v48, v49
	v_cndmask_b32_e32 v61, v48, v49, vcc
	v_mul_f32_e32 v48, v50, v64
	v_mul_f32_e32 v49, 0xbfb8aa3b, v48
	v_exp_f32_e32 v49, v49
	v_cvt_pk_bf16_f32 v50, v60, v61
	v_add_f32_e32 v49, 1.0, v49
	v_rcp_f32_e32 v49, v49
	s_nop 0
	v_mul_f32_e32 v49, v48, v49
	v_cndmask_b32_e32 v62, v48, v49, vcc
	v_mul_f32_e32 v48, v51, v64
	v_mul_f32_e32 v49, 0xbfb8aa3b, v48
	v_exp_f32_e32 v49, v49
	s_nop 0
	v_add_f32_e32 v49, 1.0, v49
	v_rcp_f32_e32 v49, v49
	s_nop 0
	v_mul_f32_e32 v49, v48, v49
	v_cndmask_b32_e32 v51, v48, v49, vcc
	v_cvt_pk_bf16_f32 v48, v52, v53
	v_cvt_pk_bf16_f32 v49, v54, v55
	v_lshl_add_u64 v[52:53], v[112:113], 0, s[2:3]
	v_add_co_u32_e64 v54, s[2:3], s82, v112
	v_cvt_pk_bf16_f32 v51, v62, v51
	s_nop 0
	v_addc_co_u32_e64 v55, s[2:3], 0, v113, s[2:3]
	global_store_dwordx4 v[54:55], v[56:59], off
	global_store_dwordx4 v[52:53], v[48:51], off offset:16
	s_nop 1
	v_fmamk_f32 v48, v150, 0x3a800000, v226
	v_cmp_gt_f32_e64 s[2:3], s33, v48
	v_mul_f32_e32 v49, 0x4b800000, v48
	s_nop 0
	v_cndmask_b32_e64 v48, v48, v49, s[2:3]
	v_rsq_f32_e32 v48, v48
	s_nop 0
	v_mul_f32_e32 v49, 0x45800000, v48
	v_cndmask_b32_e64 v48, v48, v49, s[2:3]
	v_mul_f32_e32 v44, v44, v48
	v_mul_f32_e32 v49, 0xbfb8aa3b, v44
	v_exp_f32_e32 v49, v49
	v_mul_f32_e32 v45, v45, v48
	v_mul_f32_e32 v46, v46, v48
	v_mul_f32_e32 v47, v47, v48
	v_add_f32_e32 v49, 1.0, v49
	v_rcp_f32_e32 v49, v49
	v_mul_f32_e32 v40, v40, v48
	v_mul_f32_e32 v36, v36, v48
	v_mul_f32_e32 v37, v37, v48
	v_mul_f32_e32 v49, v44, v49
	v_cndmask_b32_e32 v44, v44, v49, vcc
	v_mul_f32_e32 v49, 0xbfb8aa3b, v45
	v_exp_f32_e32 v49, v49
	v_mul_f32_e32 v38, v38, v48
	v_mul_f32_e32 v39, v39, v48
	v_mul_f32_e32 v32, v32, v48
	v_add_f32_e32 v49, 1.0, v49
	v_rcp_f32_e32 v49, v49
	s_mov_b64 s[2:3], 0x48000
	v_mul_f32_e32 v49, v45, v49
	v_cndmask_b32_e32 v45, v45, v49, vcc
	v_mul_f32_e32 v49, 0xbfb8aa3b, v46
	v_exp_f32_e32 v49, v49
	s_nop 0
	v_add_f32_e32 v49, 1.0, v49
	v_rcp_f32_e32 v49, v49
	s_nop 0
	v_mul_f32_e32 v49, v46, v49
	v_cndmask_b32_e32 v46, v46, v49, vcc
	v_mul_f32_e32 v49, 0xbfb8aa3b, v47
	v_exp_f32_e32 v49, v49
	s_nop 0
	v_add_f32_e32 v49, 1.0, v49
	v_rcp_f32_e32 v49, v49
	s_nop 0
	v_mul_f32_e32 v49, v47, v49
	v_cndmask_b32_e32 v47, v47, v49, vcc
	v_mul_f32_e32 v49, 0xbfb8aa3b, v40
	v_exp_f32_e32 v49, v49
	s_nop 0
	v_add_f32_e32 v49, 1.0, v49
	v_rcp_f32_e32 v49, v49
	s_nop 0
	v_mul_f32_e32 v49, v40, v49
	v_cndmask_b32_e32 v49, v40, v49, vcc
	v_mul_f32_e32 v40, v41, v48
	v_mul_f32_e32 v41, 0xbfb8aa3b, v40
	v_exp_f32_e32 v41, v41
	s_nop 0
	v_add_f32_e32 v41, 1.0, v41
	v_rcp_f32_e32 v41, v41
	s_nop 0
	v_mul_f32_e32 v41, v40, v41
	v_cndmask_b32_e32 v50, v40, v41, vcc
	v_mul_f32_e32 v40, v42, v48
	v_mul_f32_e32 v41, 0xbfb8aa3b, v40
	v_exp_f32_e32 v41, v41
	v_cvt_pk_bf16_f32 v42, v49, v50
	v_add_f32_e32 v41, 1.0, v41
	v_rcp_f32_e32 v41, v41
	s_nop 0
	v_mul_f32_e32 v41, v40, v41
	v_cndmask_b32_e32 v51, v40, v41, vcc
	v_mul_f32_e32 v40, v43, v48
	v_mul_f32_e32 v41, 0xbfb8aa3b, v40
	v_exp_f32_e32 v41, v41
	s_nop 0
	v_add_f32_e32 v41, 1.0, v41
	v_rcp_f32_e32 v41, v41
	s_nop 0
	v_mul_f32_e32 v41, v40, v41
	v_cndmask_b32_e32 v43, v40, v41, vcc
	v_cvt_pk_bf16_f32 v40, v44, v45
	v_mul_f32_e32 v44, 0xbfb8aa3b, v36
	v_exp_f32_e32 v44, v44
	v_cvt_pk_bf16_f32 v41, v46, v47
	v_cvt_pk_bf16_f32 v43, v51, v43
	v_add_f32_e32 v44, 1.0, v44
	v_rcp_f32_e32 v44, v44
	s_nop 0
	v_mul_f32_e32 v44, v36, v44
	v_cndmask_b32_e32 v36, v36, v44, vcc
	v_mul_f32_e32 v44, 0xbfb8aa3b, v37
	v_exp_f32_e32 v44, v44
	s_nop 0
	v_add_f32_e32 v44, 1.0, v44
	v_rcp_f32_e32 v44, v44
	s_nop 0
	v_mul_f32_e32 v44, v37, v44
	v_cndmask_b32_e32 v37, v37, v44, vcc
	v_mul_f32_e32 v44, 0xbfb8aa3b, v38
	v_exp_f32_e32 v44, v44
	s_nop 0
	v_add_f32_e32 v44, 1.0, v44
	v_rcp_f32_e32 v44, v44
	s_nop 0
	v_mul_f32_e32 v44, v38, v44
	v_cndmask_b32_e32 v38, v38, v44, vcc
	v_mul_f32_e32 v44, 0xbfb8aa3b, v39
	v_exp_f32_e32 v44, v44
	s_nop 0
	v_add_f32_e32 v44, 1.0, v44
	v_rcp_f32_e32 v44, v44
	s_nop 0
	v_mul_f32_e32 v44, v39, v44
	v_cndmask_b32_e32 v39, v39, v44, vcc
	v_mul_f32_e32 v44, 0xbfb8aa3b, v32
	v_exp_f32_e32 v44, v44
	s_nop 0
	v_add_f32_e32 v44, 1.0, v44
	v_rcp_f32_e32 v44, v44
	s_nop 0
	v_mul_f32_e32 v44, v32, v44
	v_cndmask_b32_e32 v44, v32, v44, vcc
	v_mul_f32_e32 v32, v33, v48
	v_mul_f32_e32 v33, 0xbfb8aa3b, v32
	v_exp_f32_e32 v33, v33
	s_nop 0
	v_add_f32_e32 v33, 1.0, v33
	v_rcp_f32_e32 v33, v33
	s_nop 0
	v_mul_f32_e32 v33, v32, v33
	v_cndmask_b32_e32 v45, v32, v33, vcc
	v_mul_f32_e32 v32, v34, v48
	v_mul_f32_e32 v33, 0xbfb8aa3b, v32
	v_exp_f32_e32 v33, v33
	v_cvt_pk_bf16_f32 v34, v44, v45
	v_add_f32_e32 v33, 1.0, v33
	v_rcp_f32_e32 v33, v33
	s_nop 0
	v_mul_f32_e32 v33, v32, v33
	v_cndmask_b32_e32 v46, v32, v33, vcc
	v_mul_f32_e32 v32, v35, v48
	v_mul_f32_e32 v33, 0xbfb8aa3b, v32
	v_exp_f32_e32 v33, v33
	s_nop 0
	v_add_f32_e32 v33, 1.0, v33
	v_rcp_f32_e32 v33, v33
	s_nop 0
	v_mul_f32_e32 v33, v32, v33
	v_cndmask_b32_e32 v35, v32, v33, vcc
	v_cvt_pk_bf16_f32 v32, v36, v37
	v_cvt_pk_bf16_f32 v33, v38, v39
	v_lshl_add_u64 v[36:37], v[112:113], 0, s[2:3]
	v_add_co_u32_e64 v38, s[2:3], s88, v112
	v_cvt_pk_bf16_f32 v35, v46, v35
	s_nop 0
	v_addc_co_u32_e64 v39, s[2:3], 0, v113, s[2:3]
	global_store_dwordx4 v[38:39], v[40:43], off
	global_store_dwordx4 v[36:37], v[32:35], off offset:16
	s_nop 1
	v_fmamk_f32 v32, v149, 0x3a800000, v226
; __device__ __forceinline__ unsigned pk2(float lo, float hi) { f32x2 v = {lo, hi}; bf2_t b = __builtin_convertvector(v, bf2_t); return __builtin_bit_cast(unsigned, b); }
; __device__ __forceinline__ float siluf_(float x) { return x * sigmoidf_(x); }
;     __device__ __forceinline__ void operator()(const AccT& acc, const Unit& u, int wr, int wc, int fr, int fq) const {
;     ...
;         for (int ai = 0; ai < 2; ++ai)
; #pragma unroll
;             for (int m = 0; m < 4; ++m) {
;                 const int row = row0 + ai * 128 + m * 16; const float rs = rsqrtf(rsv[ai * 4 + m] * (1.f / 1024.f) + EPS);
;                 u32x4 w[2];
; #pragma unroll
;                 for (int bj = 0; bj < 2; ++bj) {
;                     float v[8];
; #pragma unroll
;                     for (int n = 0; n < 2; ++n)
; #pragma unroll
;                         for (int j = 0; j < 4; ++j) { const float a = acc[ai][bj][m][n][j] * rs; v[n * 4 + j] = act ? siluf_(a) : a; }
;                     w[bj].x = pk2(v[0], v[1]); w[bj].y = pk2(v[2], v[3]); w[bj].z = pk2(v[4], v[5]); w[bj].w = pk2(v[6], v[7]);
;                 }
;                 u32x4* op = (u32x4*)(base + (size_t)row * DM + col0); op[0] = w[0]; op[1] = w[1];
;             }
	v_cmp_gt_f32_e64 s[2:3], s33, v32
	v_mul_f32_e32 v33, 0x4b800000, v32
	s_nop 0
	v_cndmask_b32_e64 v32, v32, v33, s[2:3]
	v_rsq_f32_e32 v32, v32
	s_nop 0
	v_mul_f32_e32 v33, 0x45800000, v32
	v_cndmask_b32_e64 v32, v32, v33, s[2:3]
	v_mul_f32_e32 v28, v28, v32
	v_mul_f32_e32 v33, 0xbfb8aa3b, v28
	v_exp_f32_e32 v33, v33
	v_mul_f32_e32 v29, v29, v32
	v_mul_f32_e32 v30, v30, v32
	v_mul_f32_e32 v31, v31, v32
	v_add_f32_e32 v33, 1.0, v33
	v_rcp_f32_e32 v33, v33
	v_mul_f32_e32 v24, v24, v32
	v_mul_f32_e32 v20, v20, v32
	v_mul_f32_e32 v21, v21, v32
	v_mul_f32_e32 v33, v28, v33
	v_cndmask_b32_e32 v28, v28, v33, vcc
	v_mul_f32_e32 v33, 0xbfb8aa3b, v29
	v_exp_f32_e32 v33, v33
	v_mul_f32_e32 v22, v22, v32
	v_mul_f32_e32 v23, v23, v32
	v_mul_f32_e32 v16, v16, v32
	v_add_f32_e32 v33, 1.0, v33
	v_rcp_f32_e32 v33, v33
	s_mov_b64 s[2:3], 0x50000
	v_mul_f32_e32 v33, v29, v33
	v_cndmask_b32_e32 v29, v29, v33, vcc
	v_mul_f32_e32 v33, 0xbfb8aa3b, v30
	v_exp_f32_e32 v33, v33
	s_nop 0
	v_add_f32_e32 v33, 1.0, v33
	v_rcp_f32_e32 v33, v33
	s_nop 0
	v_mul_f32_e32 v33, v30, v33
	v_cndmask_b32_e32 v30, v30, v33, vcc
	v_mul_f32_e32 v33, 0xbfb8aa3b, v31
	v_exp_f32_e32 v33, v33
	s_nop 0
	v_add_f32_e32 v33, 1.0, v33
	v_rcp_f32_e32 v33, v33
	s_nop 0
	v_mul_f32_e32 v33, v31, v33
	v_cndmask_b32_e32 v31, v31, v33, vcc
	v_mul_f32_e32 v33, 0xbfb8aa3b, v24
	v_exp_f32_e32 v33, v33
	s_nop 0
	v_add_f32_e32 v33, 1.0, v33
	v_rcp_f32_e32 v33, v33
	s_nop 0
	v_mul_f32_e32 v33, v24, v33
	v_cndmask_b32_e32 v33, v24, v33, vcc
	v_mul_f32_e32 v24, v25, v32
	v_mul_f32_e32 v25, 0xbfb8aa3b, v24
	v_exp_f32_e32 v25, v25
	s_nop 0
	v_add_f32_e32 v25, 1.0, v25
	v_rcp_f32_e32 v25, v25
	s_nop 0
	v_mul_f32_e32 v25, v24, v25
	v_cndmask_b32_e32 v34, v24, v25, vcc
	v_mul_f32_e32 v24, v26, v32
	v_mul_f32_e32 v25, 0xbfb8aa3b, v24
	v_exp_f32_e32 v25, v25
	v_cvt_pk_bf16_f32 v26, v33, v34
	v_add_f32_e32 v25, 1.0, v25
	v_rcp_f32_e32 v25, v25
	s_nop 0
	v_mul_f32_e32 v25, v24, v25
	v_cndmask_b32_e32 v35, v24, v25, vcc
	v_mul_f32_e32 v24, v27, v32
	v_mul_f32_e32 v25, 0xbfb8aa3b, v24
	v_exp_f32_e32 v25, v25
	s_nop 0
	v_add_f32_e32 v25, 1.0, v25
	v_rcp_f32_e32 v25, v25
	s_nop 0
	v_mul_f32_e32 v25, v24, v25
	v_cndmask_b32_e32 v27, v24, v25, vcc
	v_cvt_pk_bf16_f32 v24, v28, v29
	v_mul_f32_e32 v28, 0xbfb8aa3b, v20
	v_exp_f32_e32 v28, v28
	v_cvt_pk_bf16_f32 v25, v30, v31
	v_cvt_pk_bf16_f32 v27, v35, v27
	v_add_f32_e32 v28, 1.0, v28
	v_rcp_f32_e32 v28, v28
	s_nop 0
	v_mul_f32_e32 v28, v20, v28
	v_cndmask_b32_e32 v20, v20, v28, vcc
	v_mul_f32_e32 v28, 0xbfb8aa3b, v21
	v_exp_f32_e32 v28, v28
	s_nop 0
	v_add_f32_e32 v28, 1.0, v28
	v_rcp_f32_e32 v28, v28
	s_nop 0
	v_mul_f32_e32 v28, v21, v28
	v_cndmask_b32_e32 v21, v21, v28, vcc
	v_mul_f32_e32 v28, 0xbfb8aa3b, v22
	v_exp_f32_e32 v28, v28
	s_nop 0
	v_add_f32_e32 v28, 1.0, v28
	v_rcp_f32_e32 v28, v28
	s_nop 0
	v_mul_f32_e32 v28, v22, v28
	v_cndmask_b32_e32 v22, v22, v28, vcc
	v_mul_f32_e32 v28, 0xbfb8aa3b, v23
	v_exp_f32_e32 v28, v28
	s_nop 0
	v_add_f32_e32 v28, 1.0, v28
	v_rcp_f32_e32 v28, v28
	s_nop 0
	v_mul_f32_e32 v28, v23, v28
	v_cndmask_b32_e32 v23, v23, v28, vcc
	v_mul_f32_e32 v28, 0xbfb8aa3b, v16
	v_exp_f32_e32 v28, v28
	s_nop 0
	v_add_f32_e32 v28, 1.0, v28
	v_rcp_f32_e32 v28, v28
	s_nop 0
	v_mul_f32_e32 v28, v16, v28
	v_cndmask_b32_e32 v28, v16, v28, vcc
	v_mul_f32_e32 v16, v17, v32
	v_mul_f32_e32 v17, 0xbfb8aa3b, v16
	v_exp_f32_e32 v17, v17
	s_nop 0
	v_add_f32_e32 v17, 1.0, v17
	v_rcp_f32_e32 v17, v17
	s_nop 0
	v_mul_f32_e32 v17, v16, v17
	v_cndmask_b32_e32 v29, v16, v17, vcc
	v_mul_f32_e32 v16, v18, v32
	v_mul_f32_e32 v17, 0xbfb8aa3b, v16
	v_exp_f32_e32 v17, v17
	v_cvt_pk_bf16_f32 v18, v28, v29
	v_add_f32_e32 v17, 1.0, v17
	v_rcp_f32_e32 v17, v17
	s_nop 0
	v_mul_f32_e32 v17, v16, v17
	v_cndmask_b32_e32 v30, v16, v17, vcc
	v_mul_f32_e32 v16, v19, v32
	v_mul_f32_e32 v17, 0xbfb8aa3b, v16
	v_exp_f32_e32 v17, v17
	s_nop 0
	v_add_f32_e32 v17, 1.0, v17
	v_rcp_f32_e32 v17, v17
	s_nop 0
	v_mul_f32_e32 v17, v16, v17
	v_cndmask_b32_e32 v19, v16, v17, vcc
	v_cvt_pk_bf16_f32 v16, v20, v21
	v_cvt_pk_bf16_f32 v17, v22, v23
	v_lshl_add_u64 v[20:21], v[112:113], 0, s[2:3]
	v_add_co_u32_e64 v22, s[2:3], s89, v112
	v_cvt_pk_bf16_f32 v19, v30, v19
	s_nop 0
	v_addc_co_u32_e64 v23, s[2:3], 0, v113, s[2:3]
	global_store_dwordx4 v[22:23], v[24:27], off
	global_store_dwordx4 v[20:21], v[16:19], off offset:16
	s_nop 1
; __device__ __forceinline__ unsigned pk2(float lo, float hi) { f32x2 v = {lo, hi}; bf2_t b = __builtin_convertvector(v, bf2_t); return __builtin_bit_cast(unsigned, b); }
; __device__ __forceinline__ float siluf_(float x) { return x * sigmoidf_(x); }
;     __device__ __forceinline__ void operator()(const AccT& acc, const Unit& u, int wr, int wc, int fr, int fq) const {
;     ...
;         for (int ai = 0; ai < 2; ++ai)
; #pragma unroll
;             for (int m = 0; m < 4; ++m) {
;                 const int row = row0 + ai * 128 + m * 16; const float rs = rsqrtf(rsv[ai * 4 + m] * (1.f / 1024.f) + EPS);
;                 u32x4 w[2];
; #pragma unroll
;                 for (int bj = 0; bj < 2; ++bj) {
;                     float v[8];
; #pragma unroll
;                     for (int n = 0; n < 2; ++n)
; #pragma unroll
;                         for (int j = 0; j < 4; ++j) { const float a = acc[ai][bj][m][n][j] * rs; v[n * 4 + j] = act ? siluf_(a) : a; }
;                     w[bj].x = pk2(v[0], v[1]); w[bj].y = pk2(v[2], v[3]); w[bj].z = pk2(v[4], v[5]); w[bj].w = pk2(v[6], v[7]);
;                 }
;                 u32x4* op = (u32x4*)(base + (size_t)row * DM + col0); op[0] = w[0]; op[1] = w[1];
;             }
	v_fmamk_f32 v16, v148, 0x3a800000, v226
	v_cmp_gt_f32_e64 s[2:3], s33, v16
	v_mul_f32_e32 v17, 0x4b800000, v16
	s_nop 0
	v_cndmask_b32_e64 v16, v16, v17, s[2:3]
	v_rsq_f32_e32 v16, v16
	s_nop 0
	v_mul_f32_e32 v17, 0x45800000, v16
	v_cndmask_b32_e64 v16, v16, v17, s[2:3]
	v_mul_f32_e32 v12, v12, v16
	v_mul_f32_e32 v17, 0xbfb8aa3b, v12
	v_exp_f32_e32 v17, v17
	v_mul_f32_e32 v13, v13, v16
	v_mul_f32_e32 v14, v14, v16
	v_mul_f32_e32 v15, v15, v16
	v_add_f32_e32 v17, 1.0, v17
	v_rcp_f32_e32 v17, v17
	v_mul_f32_e32 v8, v8, v16
	v_mul_f32_e32 v4, v4, v16
	v_mul_f32_e32 v5, v5, v16
	v_mul_f32_e32 v17, v12, v17
	v_cndmask_b32_e32 v12, v12, v17, vcc
	v_mul_f32_e32 v17, 0xbfb8aa3b, v13
	v_exp_f32_e32 v17, v17
	v_mul_f32_e32 v6, v6, v16
	v_mul_f32_e32 v7, v7, v16
	v_mul_f32_e32 v0, v0, v16
	v_add_f32_e32 v17, 1.0, v17
	v_rcp_f32_e32 v17, v17
	s_mov_b64 s[2:3], -1
	v_mul_f32_e32 v17, v13, v17
	v_cndmask_b32_e32 v13, v13, v17, vcc
	v_mul_f32_e32 v17, 0xbfb8aa3b, v14
	v_exp_f32_e32 v17, v17
	s_nop 0
	v_add_f32_e32 v17, 1.0, v17
	v_rcp_f32_e32 v17, v17
	s_nop 0
	v_mul_f32_e32 v17, v14, v17
	v_cndmask_b32_e32 v14, v14, v17, vcc
	v_mul_f32_e32 v17, 0xbfb8aa3b, v15
	v_exp_f32_e32 v17, v17
	s_nop 0
	v_add_f32_e32 v17, 1.0, v17
	v_rcp_f32_e32 v17, v17
	s_nop 0
	v_mul_f32_e32 v17, v15, v17
	v_cndmask_b32_e32 v15, v15, v17, vcc
	v_mul_f32_e32 v17, 0xbfb8aa3b, v8
	v_exp_f32_e32 v17, v17
	s_nop 0
	v_add_f32_e32 v17, 1.0, v17
	v_rcp_f32_e32 v17, v17
	s_nop 0
	v_mul_f32_e32 v17, v8, v17
	v_cndmask_b32_e32 v17, v8, v17, vcc
	v_mul_f32_e32 v8, v9, v16
	v_mul_f32_e32 v9, 0xbfb8aa3b, v8
	v_exp_f32_e32 v9, v9
	s_nop 0
	v_add_f32_e32 v9, 1.0, v9
	v_rcp_f32_e32 v9, v9
	s_nop 0
	v_mul_f32_e32 v9, v8, v9
	v_cndmask_b32_e32 v18, v8, v9, vcc
	v_mul_f32_e32 v8, v10, v16
	v_mul_f32_e32 v9, 0xbfb8aa3b, v8
	v_exp_f32_e32 v9, v9
	v_cvt_pk_bf16_f32 v10, v17, v18
	v_add_f32_e32 v9, 1.0, v9
	v_rcp_f32_e32 v9, v9
	s_nop 0
	v_mul_f32_e32 v9, v8, v9
	v_cndmask_b32_e32 v19, v8, v9, vcc
	v_mul_f32_e32 v8, v11, v16
	v_mul_f32_e32 v9, 0xbfb8aa3b, v8
	v_exp_f32_e32 v9, v9
	s_nop 0
	v_add_f32_e32 v9, 1.0, v9
	v_rcp_f32_e32 v9, v9
	s_nop 0
	v_mul_f32_e32 v9, v8, v9
	v_cndmask_b32_e32 v11, v8, v9, vcc
	v_cvt_pk_bf16_f32 v8, v12, v13
	v_mul_f32_e32 v12, 0xbfb8aa3b, v4
	v_exp_f32_e32 v12, v12
	v_cvt_pk_bf16_f32 v9, v14, v15
	v_cvt_pk_bf16_f32 v11, v19, v11
	v_add_f32_e32 v12, 1.0, v12
	v_rcp_f32_e32 v12, v12
	s_nop 0
	v_mul_f32_e32 v12, v4, v12
	v_cndmask_b32_e32 v4, v4, v12, vcc
	v_mul_f32_e32 v12, 0xbfb8aa3b, v5
	v_exp_f32_e32 v12, v12
	s_nop 0
	v_add_f32_e32 v12, 1.0, v12
	v_rcp_f32_e32 v12, v12
	s_nop 0
	v_mul_f32_e32 v12, v5, v12
	v_cndmask_b32_e32 v5, v5, v12, vcc
	v_mul_f32_e32 v12, 0xbfb8aa3b, v6
	v_exp_f32_e32 v12, v12
	s_nop 0
	v_add_f32_e32 v12, 1.0, v12
	v_rcp_f32_e32 v12, v12
	s_nop 0
	v_mul_f32_e32 v12, v6, v12
	v_cndmask_b32_e32 v6, v6, v12, vcc
	v_mul_f32_e32 v12, 0xbfb8aa3b, v7
	v_exp_f32_e32 v12, v12
	s_nop 0
	v_add_f32_e32 v12, 1.0, v12
	v_rcp_f32_e32 v12, v12
	s_nop 0
	v_mul_f32_e32 v12, v7, v12
	v_cndmask_b32_e32 v7, v7, v12, vcc
	v_mul_f32_e32 v12, 0xbfb8aa3b, v0
	v_exp_f32_e32 v12, v12
	s_nop 0
	v_add_f32_e32 v12, 1.0, v12
	v_rcp_f32_e32 v12, v12
	s_nop 0
	v_mul_f32_e32 v12, v0, v12
	v_cndmask_b32_e32 v12, v0, v12, vcc
	v_mul_f32_e32 v0, v1, v16
	v_mul_f32_e32 v1, 0xbfb8aa3b, v0
	v_exp_f32_e32 v1, v1
	s_nop 0
	v_add_f32_e32 v1, 1.0, v1
	v_rcp_f32_e32 v1, v1
	s_nop 0
	v_mul_f32_e32 v1, v0, v1
	v_cndmask_b32_e32 v13, v0, v1, vcc
	v_mul_f32_e32 v0, v2, v16
	v_mul_f32_e32 v1, 0xbfb8aa3b, v0
	v_exp_f32_e32 v1, v1
	v_cvt_pk_bf16_f32 v2, v12, v13
	v_add_f32_e32 v1, 1.0, v1
	v_rcp_f32_e32 v1, v1
	s_nop 0
	v_mul_f32_e32 v1, v0, v1
	v_cndmask_b32_e32 v14, v0, v1, vcc
	v_mul_f32_e32 v0, v3, v16
	v_mul_f32_e32 v1, 0xbfb8aa3b, v0
	v_exp_f32_e32 v1, v1
	s_nop 0
	v_add_f32_e32 v1, 1.0, v1
	v_rcp_f32_e32 v1, v1
	s_nop 0
	v_mul_f32_e32 v1, v0, v1
	v_cndmask_b32_e32 v3, v0, v1, vcc
	v_cvt_pk_bf16_f32 v1, v6, v7
	v_add_co_u32_e32 v6, vcc, 0x58000, v112
	v_cvt_pk_bf16_f32 v0, v4, v5
	s_nop 0
	v_addc_co_u32_e32 v7, vcc, 0, v113, vcc
	s_andn2_b64 vcc, exec, s[0:1]
	v_cvt_pk_bf16_f32 v3, v14, v3
	v_lshl_add_u64 v[4:5], v[112:113], 0, s[90:91]
	global_store_dwordx4 v[6:7], v[8:11], off
	global_store_dwordx4 v[4:5], v[0:3], off offset:16
	s_cbranch_vccnz .LBB0_336
	s_andn2_b64 vcc, exec, s[4:5]
	s_cbranch_vccnz .LBB0_335
	s_barrier
	s_branch .LBB0_335

; #define PG8_STAGE(bufoff, gbase, voff) do { _Pragma("unroll") for (int _i = 0; _i < 2; ++_i) \
;         __builtin_amdgcn_global_load_lds((const unsigned*)((const char*)(gbase) + (voff)[_i]), (LAS unsigned*)(lds + (bufoff) + ldsw + _i * 8192), 16, 0, 0); } while (0)
; #define PG8_WAIT_V(n) asm volatile("s_waitcnt vmcnt(" #n ")" ::: "memory")
; #define PG8_BAR __builtin_amdgcn_s_barrier()
; template <class Epi, class Sched>
; __device__ __forceinline__ void gemm_phase(int wv, LAS unsigned char* lds, const Gemm g, const Sched& S, const Epi& E) {
;     ...
;     PG8_STAGE(PG8_SB(1, 0), cB + kstep, voffB); PG8_STAGE(PG8_SA(1, 0), cA + kstep, voffA); PG8_STAGE(PG8_SB(1, 1), cB + hstepB + kstep, voffB);
;     PG8_WAIT_V(6); PG8_BAR;
;     __device__ __forceinline__ void operator()(const AccT& acc, const Unit& u, int wr, int wc, int fr, int fq) const {
;     ...
;         for (int idx = 0; idx < 8; ++idx) rsv[idx] = ssq[row0 + (idx >> 2) * 128 + (idx & 3) * 16];
.LBB0_972:
	s_add_u32 s6, s0, 0xc100000
	s_addc_u32 s7, s1, 0
	s_lshl_b64 s[4:5], s[4:5], 2
	s_add_u32 s0, s0, s4
	s_addc_u32 s1, s1, s5
	s_add_u32 s4, s0, 0x100000
	s_addc_u32 s5, s1, 0
	s_lshl_b32 s0, s10, 5
	s_and_b32 s10, s0, 0x60
	s_add_i32 m0, s29, 0x18000
	v_lshl_add_u64 v[6:7], v[6:7], 0, s[74:75]
	s_lshl_b32 s11, s9, 13
	s_lshl_b32 s12, s10, 7
	s_waitcnt vmcnt(2)
	s_barrier
	global_load_lds_dwordx4 v[6:7], off
	v_lshl_add_u64 v[4:5], v[4:5], 0, s[74:75]
	s_add_i32 m0, s29, 0x1a000
	s_add_i32 s35, s29, 0x8000
	s_add_i32 s36, s29, 0xa000
	global_load_lds_dwordx4 v[4:5], off
	v_lshl_add_u64 v[0:1], v[0:1], 0, s[74:75]
	s_mov_b32 m0, s35
	s_add_u32 s0, s20, 0x40080
	global_load_lds_dwordx4 v[0:1], off
	v_lshl_add_u64 v[0:1], v[2:3], 0, s[74:75]
	s_mov_b32 m0, s36
	s_addc_u32 s1, s21, 0
	global_load_lds_dwordx4 v[0:1], off
	s_add_i32 m0, s29, 0x1c000
	v_lshl_add_u64 v[0:1], s[0:1], 0, v[188:189]
	global_load_lds_dwordx4 v[0:1], off
	v_lshl_add_u64 v[0:1], s[0:1], 0, v[128:129]
	s_add_i32 m0, s29, 0x1e000
	s_cmpk_lt_u32 s8, 0x100
	global_load_lds_dwordx4 v[0:1], off
	v_lshrrev_b32_e32 v1, 1, v8
	v_and_b32_e32 v1, 24, v1
	v_and_b32_e32 v0, 15, v8
	v_lshlrev_b32_e32 v2, 1, v1
	v_lshl_or_b32 v142, s9, 6, v0
	v_lshl_or_b32 v0, v0, 6, v2
	v_lshlrev_b32_e32 v2, 2, v8
	v_and_b32_e32 v2, 32, v2
	v_bitop3_b32 v3, v0, s11, v2 bitop3:0xde
	v_bitop3_b32 v143, v0, s12, v2 bitop3:0xde
	v_lshlrev_b32_e32 v0, 14, v13
	v_and_b32_e32 v0, 0xffff8000, v0
	v_or_b32_e32 v144, s10, v1
	v_lshl_add_u32 v0, v12, 11, v0
	v_and_b32_e32 v1, 1, v13
	v_lshl_or_b32 v0, v1, 6, v0
	v_lshl_add_u32 v134, v14, 1, v0
	v_lshlrev_b32_e32 v0, 14, v9
	v_and_b32_e32 v0, 0xffff8000, v0
	s_waitcnt vmcnt(6)
	v_lshl_add_u32 v0, v10, 11, v0
	v_and_b32_e32 v1, 1, v9
	v_lshl_or_b32 v0, v1, 6, v0
	v_readlane_b32 s0, v252, 36
	s_cselect_b64 s[8:9], -1, 0
	v_mov_b32_e32 v135, v189
	v_lshl_add_u32 v136, v11, 1, v0
	v_mov_b32_e32 v137, v189
	s_mov_b32 s72, 0
	v_add_u32_e32 v145, 0, v3
	v_readlane_b32 s37, v252, 35
	s_mov_b32 s38, s0
	v_lshl_add_u32 v234, s38, 8, v142
	v_ashrrev_i32_e32 v235, 31, v234
	v_lshl_add_u64 v[234:235], v[234:235], 2, s[4:5]
	global_load_dword v224, v[234:235], off
	global_load_dword v227, v[234:235], off offset:64
	global_load_dword v236, v[234:235], off offset:128
	global_load_dword v239, v[234:235], off offset:192
	global_load_dword v240, v[234:235], off offset:512
	global_load_dword v246, v[234:235], off offset:576
	global_load_dword v247, v[234:235], off offset:640
	global_load_dword v248, v[234:235], off offset:704
	s_barrier
	v_readlane_b32 s1, v252, 37
	s_branch .LBB0_975

; __device__ __forceinline__ unsigned pk2(float lo, float hi) { f32x2 v = {lo, hi}; bf2_t b = __builtin_convertvector(v, bf2_t); return __builtin_bit_cast(unsigned, b); }
; __device__ __forceinline__ float siluf_(float x) { return x * sigmoidf_(x); }
;     __device__ __forceinline__ void operator()(const AccT& acc, const Unit& u, int wr, int wc, int fr, int fq) const {
;         const int row0 = u.pm * 256 + wr * 64 + fr, col0 = u.pn * 128 + wc * 32 + 8 * fq;
;         float rsv[8];
; #pragma unroll
;         for (int idx = 0; idx < 8; ++idx) rsv[idx] = ssq[row0 + (idx >> 2) * 128 + (idx & 3) * 16];
; #pragma unroll
;         for (int ai = 0; ai < 2; ++ai)
; #pragma unroll
;             for (int m = 0; m < 4; ++m) {
;                 const int row = row0 + ai * 128 + m * 16; const float rs = rsqrtf(rsv[ai * 4 + m] * (1.f / 1024.f) + EPS);
;                 float h[8];
; #pragma unroll
;                 for (int n = 0; n < 2; ++n)
; #pragma unroll
;                     for (int j = 0; j < 4; ++j) { const float a = acc[ai][0][m][n][j] * rs, b = acc[ai][1][m][n][j] * rs; h[n * 4 + j] = siluf_(a) * b; }
;                 u32x4 w; w.x = pk2(h[0], h[1]); w.y = pk2(h[2], h[3]); w.z = pk2(h[4], h[5]); w.w = pk2(h[6], h[7]);
;                 *(u32x4*)(H + (size_t)row * DFF + col0) = w;
.LBB0_981:
	v_lshl_add_u32 v138, s38, 8, v142
	v_ashrrev_i32_e32 v139, 31, v138
	v_lshl_add_u64 v[140:141], v[138:139], 2, s[4:5]
	v_lshl_or_b32 v140, s37, 7, v144
	v_ashrrev_i32_e32 v141, 31, v140
	s_movk_i32 s11, 0x1600
	v_add_u32_e32 v148, 0x80, v138
	s_waitcnt vmcnt(0)
	v_mov_b32_e32 v152, v224
	v_mov_b32_e32 v153, v227
	v_mov_b32_e32 v151, v236
	v_mov_b32_e32 v150, v239
	v_mov_b32_e32 v149, v240
	v_mov_b32_e32 v147, v246
	v_mov_b32_e32 v146, v247
	v_mov_b32_e32 v139, v248
	s_and_b32 s32, s10, 0x7f
	v_lshl_add_u32 v234, s32, 8, v142
	v_ashrrev_i32_e32 v235, 31, v234
	v_lshl_add_u64 v[234:235], v[234:235], 2, s[4:5]
	global_load_dword v224, v[234:235], off
	global_load_dword v227, v[234:235], off offset:64
	global_load_dword v236, v[234:235], off offset:128
	global_load_dword v239, v[234:235], off offset:192
	global_load_dword v240, v[234:235], off offset:512
	global_load_dword v246, v[234:235], off offset:576
	global_load_dword v247, v[234:235], off offset:640
	global_load_dword v248, v[234:235], off offset:704
	v_fmamk_f32 v152, v152, 0x3a800000, v226
	v_cmp_gt_f32_e32 vcc, s33, v152
	v_mul_f32_e32 v154, 0x4b800000, v152
	s_nop 0
	v_cndmask_b32_e32 v152, v152, v154, vcc
	v_rsq_f32_e32 v152, v152
	s_nop 0
	v_mul_f32_e32 v154, 0x45800000, v152
	v_cndmask_b32_e32 v152, v152, v154, vcc
	v_pk_mul_f32 v[124:125], v[124:125], v[152:153] op_sel_hi:[1,0]
	v_pk_mul_f32 v[116:117], v[116:117], v[152:153] op_sel_hi:[1,0]
	v_mul_f32_e32 v154, 0xbfb8aa3b, v124
	v_mul_f32_e32 v155, 0xbfb8aa3b, v125
	v_exp_f32_e32 v154, v154
	v_exp_f32_e32 v155, v155
	v_pk_mul_f32 v[118:119], v[118:119], v[152:153] op_sel_hi:[1,0]
	v_pk_mul_f32 v[120:121], v[120:121], v[152:153] op_sel_hi:[1,0]
	v_add_f32_e32 v154, 1.0, v154
	v_add_f32_e32 v155, 1.0, v155
	v_rcp_f32_e32 v154, v154
	v_rcp_f32_e32 v155, v155
	v_pk_mul_f32 v[112:113], v[112:113], v[152:153] op_sel_hi:[1,0]
	v_pk_mul_f32 v[114:115], v[114:115], v[152:153] op_sel_hi:[1,0]
	v_pk_mul_f32 v[124:125], v[124:125], v[154:155]
	s_nop 0
	v_pk_mul_f32 v[116:117], v[116:117], v[124:125]
	v_pk_mul_f32 v[124:125], v[126:127], v[152:153] op_sel_hi:[1,0]
	s_nop 0
	v_mul_f32_e32 v126, 0xbfb8aa3b, v124
	v_mul_f32_e32 v127, 0xbfb8aa3b, v125
	v_exp_f32_e32 v126, v126
	v_exp_f32_e32 v127, v127
	v_add_f32_e32 v126, 1.0, v126
	v_add_f32_e32 v127, 1.0, v127
	v_rcp_f32_e32 v126, v126
	v_rcp_f32_e32 v127, v127
	s_nop 0
	v_pk_mul_f32 v[124:125], v[124:125], v[126:127]
	s_nop 0
	v_pk_mul_f32 v[118:119], v[118:119], v[124:125]
	v_mul_f32_e32 v124, 0xbfb8aa3b, v120
	v_mul_f32_e32 v125, 0xbfb8aa3b, v121
	v_exp_f32_e32 v124, v124
	v_exp_f32_e32 v125, v125
	v_add_f32_e32 v124, 1.0, v124
	v_add_f32_e32 v125, 1.0, v125
	v_rcp_f32_e32 v124, v124
	v_rcp_f32_e32 v125, v125
	s_nop 0
	v_pk_mul_f32 v[120:121], v[120:121], v[124:125]
	s_nop 0
	v_pk_mul_f32 v[120:121], v[112:113], v[120:121]
	v_pk_mul_f32 v[112:113], v[122:123], v[152:153] op_sel_hi:[1,0]
	s_nop 0
	v_mul_f32_e32 v122, 0xbfb8aa3b, v112
	v_mul_f32_e32 v123, 0xbfb8aa3b, v113
	v_exp_f32_e32 v122, v122
	v_exp_f32_e32 v123, v123
	v_add_f32_e32 v122, 1.0, v122
	v_add_f32_e32 v123, 1.0, v123
	v_rcp_f32_e32 v122, v122
	v_rcp_f32_e32 v123, v123
	s_nop 0
	v_pk_mul_f32 v[112:113], v[112:113], v[122:123]
	s_nop 0
	v_pk_mul_f32 v[122:123], v[114:115], v[112:113]
	v_cvt_pk_bf16_f32 v112, v116, v117
	v_mov_b64_e32 v[116:117], s[6:7]
	v_cvt_pk_bf16_f32 v113, v118, v119
	v_cvt_pk_bf16_f32 v114, v120, v121
	v_mad_i64_i32 v[120:121], s[18:19], v138, s11, v[116:117]
	v_lshlrev_b64 v[118:119], 1, v[140:141]
	v_cvt_pk_bf16_f32 v115, v122, v123
	v_lshl_add_u64 v[120:121], v[120:121], 0, v[118:119]
	global_store_dwordx4 v[120:121], v[112:115], off
	s_nop 1
	v_fmamk_f32 v112, v153, 0x3a800000, v226
	v_cmp_gt_f32_e32 vcc, s33, v112
	v_mul_f32_e32 v113, 0x4b800000, v112
	s_nop 0
	v_cndmask_b32_e32 v112, v112, v113, vcc
	v_rsq_f32_e32 v112, v112
	s_nop 0
	v_mul_f32_e32 v113, 0x45800000, v112
	v_cndmask_b32_e32 v112, v112, v113, vcc
	v_pk_mul_f32 v[108:109], v[108:109], v[112:113] op_sel_hi:[1,0]
	s_nop 0
	v_mul_f32_e32 v113, 0xbfb8aa3b, v108
	v_exp_f32_e32 v113, v113
	s_nop 0
	v_add_f32_e32 v113, 1.0, v113
	v_rcp_f32_e32 v114, v113
	v_pk_mul_f32 v[104:105], v[104:105], v[112:113] op_sel_hi:[1,0]
	v_mul_f32_e32 v113, 0xbfb8aa3b, v109
	v_exp_f32_e32 v113, v113
	s_nop 0
	v_add_f32_e32 v113, 1.0, v113
	v_rcp_f32_e32 v115, v113
	v_pk_mul_f32 v[106:107], v[106:107], v[112:113] op_sel_hi:[1,0]
	v_pk_mul_f32 v[100:101], v[100:101], v[112:113] op_sel_hi:[1,0]
	v_pk_mul_f32 v[96:97], v[96:97], v[112:113] op_sel_hi:[1,0]
	v_pk_mul_f32 v[108:109], v[108:109], v[114:115]
	v_pk_mul_f32 v[98:99], v[98:99], v[112:113] op_sel_hi:[1,0]
	v_pk_mul_f32 v[104:105], v[104:105], v[108:109]
	v_pk_mul_f32 v[108:109], v[110:111], v[112:113] op_sel_hi:[1,0]
	s_nop 0
	v_mul_f32_e32 v110, 0xbfb8aa3b, v108
	v_mul_f32_e32 v111, 0xbfb8aa3b, v109
	v_exp_f32_e32 v110, v110
	v_exp_f32_e32 v111, v111
	v_add_f32_e32 v110, 1.0, v110
	v_add_f32_e32 v111, 1.0, v111
	v_rcp_f32_e32 v110, v110
	v_rcp_f32_e32 v111, v111
	s_nop 0
	v_pk_mul_f32 v[108:109], v[108:109], v[110:111]
	s_nop 0
	v_pk_mul_f32 v[106:107], v[106:107], v[108:109]
	v_mul_f32_e32 v108, 0xbfb8aa3b, v100
	v_mul_f32_e32 v109, 0xbfb8aa3b, v101
	v_exp_f32_e32 v108, v108
	v_exp_f32_e32 v109, v109
	v_add_f32_e32 v108, 1.0, v108
	v_add_f32_e32 v109, 1.0, v109
	v_rcp_f32_e32 v108, v108
	v_rcp_f32_e32 v109, v109
	s_nop 0
	v_pk_mul_f32 v[100:101], v[100:101], v[108:109]
	s_nop 0
	v_pk_mul_f32 v[100:101], v[96:97], v[100:101]
	v_pk_mul_f32 v[96:97], v[102:103], v[112:113] op_sel_hi:[1,0]
	v_or_b32_e32 v108, 16, v138
	v_mul_f32_e32 v102, 0xbfb8aa3b, v96
	v_mul_f32_e32 v103, 0xbfb8aa3b, v97
; __device__ __forceinline__ unsigned pk2(float lo, float hi) { f32x2 v = {lo, hi}; bf2_t b = __builtin_convertvector(v, bf2_t); return __builtin_bit_cast(unsigned, b); }
; __device__ __forceinline__ float siluf_(float x) { return x * sigmoidf_(x); }
;     __device__ __forceinline__ void operator()(const AccT& acc, const Unit& u, int wr, int wc, int fr, int fq) const {
;     ...
;         for (int ai = 0; ai < 2; ++ai)
; #pragma unroll
;             for (int m = 0; m < 4; ++m) {
;                 const int row = row0 + ai * 128 + m * 16; const float rs = rsqrtf(rsv[ai * 4 + m] * (1.f / 1024.f) + EPS);
;                 float h[8];
; #pragma unroll
;                 for (int n = 0; n < 2; ++n)
; #pragma unroll
;                     for (int j = 0; j < 4; ++j) { const float a = acc[ai][0][m][n][j] * rs, b = acc[ai][1][m][n][j] * rs; h[n * 4 + j] = siluf_(a) * b; }
;                 u32x4 w; w.x = pk2(h[0], h[1]); w.y = pk2(h[2], h[3]); w.z = pk2(h[4], h[5]); w.w = pk2(h[6], h[7]);
;                 *(u32x4*)(H + (size_t)row * DFF + col0) = w;
;             }
	v_exp_f32_e32 v102, v102
	v_exp_f32_e32 v103, v103
	v_add_f32_e32 v102, 1.0, v102
	v_add_f32_e32 v103, 1.0, v103
	v_rcp_f32_e32 v102, v102
	v_rcp_f32_e32 v103, v103
	s_nop 0
	v_pk_mul_f32 v[96:97], v[96:97], v[102:103]
	s_nop 0
	v_pk_mul_f32 v[102:103], v[98:99], v[96:97]
	v_cvt_pk_bf16_f32 v98, v100, v101
	v_mad_i64_i32 v[100:101], s[18:19], v108, s11, v[116:117]
	v_cvt_pk_bf16_f32 v96, v104, v105
	v_cvt_pk_bf16_f32 v97, v106, v107
	v_cvt_pk_bf16_f32 v99, v102, v103
	v_lshl_add_u64 v[100:101], v[100:101], 0, v[118:119]
	global_store_dwordx4 v[100:101], v[96:99], off
	s_nop 1
	v_fmamk_f32 v96, v151, 0x3a800000, v226
	v_cmp_gt_f32_e32 vcc, s33, v96
	v_mul_f32_e32 v97, 0x4b800000, v96
	s_nop 0
	v_cndmask_b32_e32 v96, v96, v97, vcc
	v_rsq_f32_e32 v96, v96
	s_nop 0
	v_mul_f32_e32 v97, 0x45800000, v96
	v_cndmask_b32_e32 v96, v96, v97, vcc
	v_pk_mul_f32 v[92:93], v[92:93], v[96:97] op_sel_hi:[1,0]
	s_nop 0
	v_mul_f32_e32 v97, 0xbfb8aa3b, v92
	v_exp_f32_e32 v97, v97
	s_nop 0
	v_add_f32_e32 v97, 1.0, v97
	v_rcp_f32_e32 v98, v97
	v_pk_mul_f32 v[88:89], v[88:89], v[96:97] op_sel_hi:[1,0]
	v_mul_f32_e32 v97, 0xbfb8aa3b, v93
	v_exp_f32_e32 v97, v97
	s_nop 0
	v_add_f32_e32 v97, 1.0, v97
	v_rcp_f32_e32 v99, v97
	v_pk_mul_f32 v[90:91], v[90:91], v[96:97] op_sel_hi:[1,0]
	v_pk_mul_f32 v[84:85], v[84:85], v[96:97] op_sel_hi:[1,0]
	v_pk_mul_f32 v[80:81], v[80:81], v[96:97] op_sel_hi:[1,0]
	v_pk_mul_f32 v[92:93], v[92:93], v[98:99]
	v_pk_mul_f32 v[82:83], v[82:83], v[96:97] op_sel_hi:[1,0]
	v_pk_mul_f32 v[88:89], v[88:89], v[92:93]
	v_pk_mul_f32 v[92:93], v[94:95], v[96:97] op_sel_hi:[1,0]
	s_nop 0
	v_mul_f32_e32 v94, 0xbfb8aa3b, v92
	v_mul_f32_e32 v95, 0xbfb8aa3b, v93
	v_exp_f32_e32 v94, v94
	v_exp_f32_e32 v95, v95
	v_add_f32_e32 v94, 1.0, v94
	v_add_f32_e32 v95, 1.0, v95
	v_rcp_f32_e32 v94, v94
	v_rcp_f32_e32 v95, v95
	s_nop 0
	v_pk_mul_f32 v[92:93], v[92:93], v[94:95]
	s_nop 0
	v_pk_mul_f32 v[90:91], v[90:91], v[92:93]
	v_mul_f32_e32 v92, 0xbfb8aa3b, v84
	v_mul_f32_e32 v93, 0xbfb8aa3b, v85
	v_exp_f32_e32 v92, v92
	v_exp_f32_e32 v93, v93
	v_add_f32_e32 v92, 1.0, v92
	v_add_f32_e32 v93, 1.0, v93
	v_rcp_f32_e32 v92, v92
	v_rcp_f32_e32 v93, v93
	s_nop 0
	v_pk_mul_f32 v[84:85], v[84:85], v[92:93]
	s_nop 0
	v_pk_mul_f32 v[84:85], v[80:81], v[84:85]
	v_pk_mul_f32 v[80:81], v[86:87], v[96:97] op_sel_hi:[1,0]
	v_or_b32_e32 v92, 32, v138
	v_mul_f32_e32 v86, 0xbfb8aa3b, v80
	v_mul_f32_e32 v87, 0xbfb8aa3b, v81
	v_exp_f32_e32 v86, v86
	v_exp_f32_e32 v87, v87
	v_add_f32_e32 v86, 1.0, v86
	v_add_f32_e32 v87, 1.0, v87
	v_rcp_f32_e32 v86, v86
	v_rcp_f32_e32 v87, v87
	s_nop 0
	v_pk_mul_f32 v[80:81], v[80:81], v[86:87]
	s_nop 0
	v_pk_mul_f32 v[86:87], v[82:83], v[80:81]
	v_cvt_pk_bf16_f32 v82, v84, v85
	v_mad_i64_i32 v[84:85], s[18:19], v92, s11, v[116:117]
	v_cvt_pk_bf16_f32 v80, v88, v89
	v_cvt_pk_bf16_f32 v81, v90, v91
	v_cvt_pk_bf16_f32 v83, v86, v87
	v_lshl_add_u64 v[84:85], v[84:85], 0, v[118:119]
	global_store_dwordx4 v[84:85], v[80:83], off
	s_nop 1
	v_fmamk_f32 v80, v150, 0x3a800000, v226
	v_cmp_gt_f32_e32 vcc, s33, v80
	v_mul_f32_e32 v81, 0x4b800000, v80
	s_nop 0
	v_cndmask_b32_e32 v80, v80, v81, vcc
	v_rsq_f32_e32 v80, v80
	s_nop 0
	v_mul_f32_e32 v81, 0x45800000, v80
	v_cndmask_b32_e32 v80, v80, v81, vcc
	v_pk_mul_f32 v[76:77], v[76:77], v[80:81] op_sel_hi:[1,0]
	s_nop 0
	v_mul_f32_e32 v81, 0xbfb8aa3b, v76
	v_exp_f32_e32 v81, v81
	s_nop 0
	v_add_f32_e32 v81, 1.0, v81
	v_rcp_f32_e32 v82, v81
	v_pk_mul_f32 v[72:73], v[72:73], v[80:81] op_sel_hi:[1,0]
	v_mul_f32_e32 v81, 0xbfb8aa3b, v77
	v_exp_f32_e32 v81, v81
	s_nop 0
	v_add_f32_e32 v81, 1.0, v81
	v_rcp_f32_e32 v83, v81
	v_pk_mul_f32 v[74:75], v[74:75], v[80:81] op_sel_hi:[1,0]
	v_pk_mul_f32 v[68:69], v[68:69], v[80:81] op_sel_hi:[1,0]
	v_pk_mul_f32 v[64:65], v[64:65], v[80:81] op_sel_hi:[1,0]
	v_pk_mul_f32 v[76:77], v[76:77], v[82:83]
	v_pk_mul_f32 v[66:67], v[66:67], v[80:81] op_sel_hi:[1,0]
	v_pk_mul_f32 v[72:73], v[72:73], v[76:77]
	v_pk_mul_f32 v[76:77], v[78:79], v[80:81] op_sel_hi:[1,0]
	s_nop 0
	v_mul_f32_e32 v78, 0xbfb8aa3b, v76
	v_mul_f32_e32 v79, 0xbfb8aa3b, v77
	v_exp_f32_e32 v78, v78
	v_exp_f32_e32 v79, v79
	v_add_f32_e32 v78, 1.0, v78
	v_add_f32_e32 v79, 1.0, v79
	v_rcp_f32_e32 v78, v78
	v_rcp_f32_e32 v79, v79
	s_nop 0
	v_pk_mul_f32 v[76:77], v[76:77], v[78:79]
	s_nop 0
	v_pk_mul_f32 v[74:75], v[74:75], v[76:77]
	v_mul_f32_e32 v76, 0xbfb8aa3b, v68
	v_mul_f32_e32 v77, 0xbfb8aa3b, v69
	v_exp_f32_e32 v76, v76
	v_exp_f32_e32 v77, v77
	v_add_f32_e32 v76, 1.0, v76
	v_add_f32_e32 v77, 1.0, v77
	v_rcp_f32_e32 v76, v76
	v_rcp_f32_e32 v77, v77
	s_nop 0
	v_pk_mul_f32 v[68:69], v[68:69], v[76:77]
	s_nop 0
	v_pk_mul_f32 v[68:69], v[64:65], v[68:69]
	v_pk_mul_f32 v[64:65], v[70:71], v[80:81] op_sel_hi:[1,0]
	v_or_b32_e32 v76, 48, v138
	v_mul_f32_e32 v70, 0xbfb8aa3b, v64
	v_mul_f32_e32 v71, 0xbfb8aa3b, v65
	v_exp_f32_e32 v70, v70
	v_exp_f32_e32 v71, v71
	v_add_f32_e32 v70, 1.0, v70
	v_add_f32_e32 v71, 1.0, v71
	v_rcp_f32_e32 v70, v70
	v_rcp_f32_e32 v71, v71
	s_nop 0
	v_pk_mul_f32 v[64:65], v[64:65], v[70:71]
	s_nop 0
	v_pk_mul_f32 v[70:71], v[66:67], v[64:65]
	v_cvt_pk_bf16_f32 v66, v68, v69
	v_mad_i64_i32 v[68:69], s[18:19], v76, s11, v[116:117]
	v_cvt_pk_bf16_f32 v64, v72, v73
	v_cvt_pk_bf16_f32 v65, v74, v75
	v_cvt_pk_bf16_f32 v67, v70, v71
	v_lshl_add_u64 v[68:69], v[68:69], 0, v[118:119]
	global_store_dwordx4 v[68:69], v[64:67], off
	s_nop 1
	v_fmamk_f32 v64, v149, 0x3a800000, v226
	v_cmp_gt_f32_e32 vcc, s33, v64
	v_mul_f32_e32 v65, 0x4b800000, v64
	s_nop 0
	v_cndmask_b32_e32 v64, v64, v65, vcc
	v_rsq_f32_e32 v64, v64
	s_nop 0
	v_mul_f32_e32 v65, 0x45800000, v64
	v_cndmask_b32_e32 v64, v64, v65, vcc
; __device__ __forceinline__ unsigned pk2(float lo, float hi) { f32x2 v = {lo, hi}; bf2_t b = __builtin_convertvector(v, bf2_t); return __builtin_bit_cast(unsigned, b); }
; __device__ __forceinline__ float siluf_(float x) { return x * sigmoidf_(x); }
;     __device__ __forceinline__ void operator()(const AccT& acc, const Unit& u, int wr, int wc, int fr, int fq) const {
;     ...
;         for (int ai = 0; ai < 2; ++ai)
; #pragma unroll
;             for (int m = 0; m < 4; ++m) {
;                 const int row = row0 + ai * 128 + m * 16; const float rs = rsqrtf(rsv[ai * 4 + m] * (1.f / 1024.f) + EPS);
;                 float h[8];
; #pragma unroll
;                 for (int n = 0; n < 2; ++n)
; #pragma unroll
;                     for (int j = 0; j < 4; ++j) { const float a = acc[ai][0][m][n][j] * rs, b = acc[ai][1][m][n][j] * rs; h[n * 4 + j] = siluf_(a) * b; }
;                 u32x4 w; w.x = pk2(h[0], h[1]); w.y = pk2(h[2], h[3]); w.z = pk2(h[4], h[5]); w.w = pk2(h[6], h[7]);
;                 *(u32x4*)(H + (size_t)row * DFF + col0) = w;
;             }
	v_pk_mul_f32 v[60:61], v[60:61], v[64:65] op_sel_hi:[1,0]
	s_nop 0
	v_mul_f32_e32 v65, 0xbfb8aa3b, v60
	v_exp_f32_e32 v65, v65
	s_nop 0
	v_add_f32_e32 v65, 1.0, v65
	v_rcp_f32_e32 v66, v65
	v_pk_mul_f32 v[56:57], v[56:57], v[64:65] op_sel_hi:[1,0]
	v_mul_f32_e32 v65, 0xbfb8aa3b, v61
	v_exp_f32_e32 v65, v65
	s_nop 0
	v_add_f32_e32 v65, 1.0, v65
	v_rcp_f32_e32 v67, v65
	v_pk_mul_f32 v[58:59], v[58:59], v[64:65] op_sel_hi:[1,0]
	v_pk_mul_f32 v[52:53], v[52:53], v[64:65] op_sel_hi:[1,0]
	v_pk_mul_f32 v[48:49], v[48:49], v[64:65] op_sel_hi:[1,0]
	v_pk_mul_f32 v[60:61], v[60:61], v[66:67]
	v_pk_mul_f32 v[50:51], v[50:51], v[64:65] op_sel_hi:[1,0]
	v_pk_mul_f32 v[56:57], v[56:57], v[60:61]
	v_pk_mul_f32 v[60:61], v[62:63], v[64:65] op_sel_hi:[1,0]
	s_nop 0
	v_mul_f32_e32 v62, 0xbfb8aa3b, v60
	v_mul_f32_e32 v63, 0xbfb8aa3b, v61
	v_exp_f32_e32 v62, v62
	v_exp_f32_e32 v63, v63
	v_add_f32_e32 v62, 1.0, v62
	v_add_f32_e32 v63, 1.0, v63
	v_rcp_f32_e32 v62, v62
	v_rcp_f32_e32 v63, v63
	s_nop 0
	v_pk_mul_f32 v[60:61], v[60:61], v[62:63]
	s_nop 0
	v_pk_mul_f32 v[58:59], v[58:59], v[60:61]
	v_mul_f32_e32 v60, 0xbfb8aa3b, v52
	v_mul_f32_e32 v61, 0xbfb8aa3b, v53
	v_exp_f32_e32 v60, v60
	v_exp_f32_e32 v61, v61
	v_add_f32_e32 v60, 1.0, v60
	v_add_f32_e32 v61, 1.0, v61
	v_rcp_f32_e32 v60, v60
	v_rcp_f32_e32 v61, v61
	s_nop 0
	v_pk_mul_f32 v[52:53], v[52:53], v[60:61]
	s_nop 0
	v_pk_mul_f32 v[52:53], v[48:49], v[52:53]
	v_pk_mul_f32 v[48:49], v[54:55], v[64:65] op_sel_hi:[1,0]
	s_nop 0
	v_mul_f32_e32 v54, 0xbfb8aa3b, v48
	v_mul_f32_e32 v55, 0xbfb8aa3b, v49
	v_exp_f32_e32 v54, v54
	v_exp_f32_e32 v55, v55
	v_add_f32_e32 v54, 1.0, v54
	v_add_f32_e32 v55, 1.0, v55
	v_rcp_f32_e32 v54, v54
	v_rcp_f32_e32 v55, v55
	s_nop 0
	v_pk_mul_f32 v[48:49], v[48:49], v[54:55]
	s_nop 0
	v_pk_mul_f32 v[54:55], v[50:51], v[48:49]
	v_cvt_pk_bf16_f32 v50, v52, v53
	v_mad_i64_i32 v[52:53], s[18:19], v148, s11, v[116:117]
	v_cvt_pk_bf16_f32 v48, v56, v57
	v_cvt_pk_bf16_f32 v49, v58, v59
	v_cvt_pk_bf16_f32 v51, v54, v55
	v_lshl_add_u64 v[52:53], v[52:53], 0, v[118:119]
	global_store_dwordx4 v[52:53], v[48:51], off
	s_nop 1
	v_fmamk_f32 v48, v147, 0x3a800000, v226
	v_cmp_gt_f32_e32 vcc, s33, v48
	v_mul_f32_e32 v49, 0x4b800000, v48
	s_nop 0
	v_cndmask_b32_e32 v48, v48, v49, vcc
	v_rsq_f32_e32 v48, v48
	s_nop 0
	v_mul_f32_e32 v49, 0x45800000, v48
	v_cndmask_b32_e32 v48, v48, v49, vcc
	v_pk_mul_f32 v[44:45], v[44:45], v[48:49] op_sel_hi:[1,0]
	s_nop 0
	v_mul_f32_e32 v49, 0xbfb8aa3b, v44
	v_exp_f32_e32 v49, v49
	s_nop 0
	v_add_f32_e32 v49, 1.0, v49
	v_rcp_f32_e32 v50, v49
	v_pk_mul_f32 v[40:41], v[40:41], v[48:49] op_sel_hi:[1,0]
	v_mul_f32_e32 v49, 0xbfb8aa3b, v45
	v_exp_f32_e32 v49, v49
	s_nop 0
	v_add_f32_e32 v49, 1.0, v49
	v_rcp_f32_e32 v51, v49
	v_pk_mul_f32 v[42:43], v[42:43], v[48:49] op_sel_hi:[1,0]
	v_pk_mul_f32 v[36:37], v[36:37], v[48:49] op_sel_hi:[1,0]
	v_pk_mul_f32 v[32:33], v[32:33], v[48:49] op_sel_hi:[1,0]
	v_pk_mul_f32 v[44:45], v[44:45], v[50:51]
	v_pk_mul_f32 v[34:35], v[34:35], v[48:49] op_sel_hi:[1,0]
	v_pk_mul_f32 v[40:41], v[40:41], v[44:45]
	v_pk_mul_f32 v[44:45], v[46:47], v[48:49] op_sel_hi:[1,0]
	s_nop 0
	v_mul_f32_e32 v46, 0xbfb8aa3b, v44
	v_mul_f32_e32 v47, 0xbfb8aa3b, v45
	v_exp_f32_e32 v46, v46
	v_exp_f32_e32 v47, v47
	v_add_f32_e32 v46, 1.0, v46
	v_add_f32_e32 v47, 1.0, v47
	v_rcp_f32_e32 v46, v46
	v_rcp_f32_e32 v47, v47
	s_nop 0
	v_pk_mul_f32 v[44:45], v[44:45], v[46:47]
	s_nop 0
	v_pk_mul_f32 v[42:43], v[42:43], v[44:45]
	v_mul_f32_e32 v44, 0xbfb8aa3b, v36
	v_mul_f32_e32 v45, 0xbfb8aa3b, v37
	v_exp_f32_e32 v44, v44
	v_exp_f32_e32 v45, v45
	v_add_f32_e32 v44, 1.0, v44
	v_add_f32_e32 v45, 1.0, v45
	v_rcp_f32_e32 v44, v44
	v_rcp_f32_e32 v45, v45
	s_nop 0
	v_pk_mul_f32 v[36:37], v[36:37], v[44:45]
	s_nop 0
	v_pk_mul_f32 v[36:37], v[32:33], v[36:37]
	v_pk_mul_f32 v[32:33], v[38:39], v[48:49] op_sel_hi:[1,0]
	v_add_u32_e32 v44, 0x90, v138
	v_mul_f32_e32 v38, 0xbfb8aa3b, v32
	v_mul_f32_e32 v39, 0xbfb8aa3b, v33
	v_exp_f32_e32 v38, v38
	v_exp_f32_e32 v39, v39
	v_add_f32_e32 v38, 1.0, v38
	v_add_f32_e32 v39, 1.0, v39
	v_rcp_f32_e32 v38, v38
	v_rcp_f32_e32 v39, v39
	s_nop 0
	v_pk_mul_f32 v[32:33], v[32:33], v[38:39]
	s_nop 0
	v_pk_mul_f32 v[38:39], v[34:35], v[32:33]
	v_cvt_pk_bf16_f32 v34, v36, v37
	v_mad_i64_i32 v[36:37], s[18:19], v44, s11, v[116:117]
	v_cvt_pk_bf16_f32 v32, v40, v41
	v_cvt_pk_bf16_f32 v33, v42, v43
	v_cvt_pk_bf16_f32 v35, v38, v39
	v_lshl_add_u64 v[36:37], v[36:37], 0, v[118:119]
	global_store_dwordx4 v[36:37], v[32:35], off
	s_nop 1
	v_fmamk_f32 v32, v146, 0x3a800000, v226
	v_cmp_gt_f32_e32 vcc, s33, v32
	v_mul_f32_e32 v33, 0x4b800000, v32
	s_nop 0
	v_cndmask_b32_e32 v32, v32, v33, vcc
	v_rsq_f32_e32 v32, v32
; __device__ __forceinline__ unsigned pk2(float lo, float hi) { f32x2 v = {lo, hi}; bf2_t b = __builtin_convertvector(v, bf2_t); return __builtin_bit_cast(unsigned, b); }
; __device__ __forceinline__ float siluf_(float x) { return x * sigmoidf_(x); }
; #define PG8_BAR __builtin_amdgcn_s_barrier()
; template <class Epi, class Sched>
; __device__ __forceinline__ void gemm_phase(int wv, LAS unsigned char* lds, const Gemm g, const Sched& S, const Epi& E) {
;     ...
;         }
;         if (wr == 0) PG8_BAR;
;         E(acc, cur, wr, wc, fr, fq);
;         if (!has_next) break;
; #pragma unroll
;         for (int a = 0; a < 2; ++a)
; #pragma unroll
;             for (int b = 0; b < 2; ++b)
; #pragma unroll
;                 for (int m = 0; m < 4; ++m)
; #pragma unroll
;                     for (int n = 0; n < 2; ++n) acc[a][b][m][n] = (f32x4){0.f, 0.f, 0.f, 0.f};
;         cur = nxt; cA = nA; cB = nB; ++ui;
;         if (wr == 1) PG8_BAR;
;     __device__ __forceinline__ void operator()(const AccT& acc, const Unit& u, int wr, int wc, int fr, int fq) const {
;     ...
;         for (int ai = 0; ai < 2; ++ai)
; #pragma unroll
;             for (int m = 0; m < 4; ++m) {
;                 const int row = row0 + ai * 128 + m * 16; const float rs = rsqrtf(rsv[ai * 4 + m] * (1.f / 1024.f) + EPS);
;                 float h[8];
; #pragma unroll
;                 for (int n = 0; n < 2; ++n)
; #pragma unroll
;                     for (int j = 0; j < 4; ++j) { const float a = acc[ai][0][m][n][j] * rs, b = acc[ai][1][m][n][j] * rs; h[n * 4 + j] = siluf_(a) * b; }
;                 u32x4 w; w.x = pk2(h[0], h[1]); w.y = pk2(h[2], h[3]); w.z = pk2(h[4], h[5]); w.w = pk2(h[6], h[7]);
;                 *(u32x4*)(H + (size_t)row * DFF + col0) = w;
;             }
	s_nop 0
	v_mul_f32_e32 v33, 0x45800000, v32
	v_cndmask_b32_e32 v32, v32, v33, vcc
	v_pk_mul_f32 v[28:29], v[28:29], v[32:33] op_sel_hi:[1,0]
	s_nop 0
	v_mul_f32_e32 v33, 0xbfb8aa3b, v28
	v_exp_f32_e32 v33, v33
	s_nop 0
	v_add_f32_e32 v33, 1.0, v33
	v_rcp_f32_e32 v34, v33
	v_pk_mul_f32 v[24:25], v[24:25], v[32:33] op_sel_hi:[1,0]
	v_mul_f32_e32 v33, 0xbfb8aa3b, v29
	v_exp_f32_e32 v33, v33
	s_nop 0
	v_add_f32_e32 v33, 1.0, v33
	v_rcp_f32_e32 v35, v33
	v_pk_mul_f32 v[26:27], v[26:27], v[32:33] op_sel_hi:[1,0]
	v_pk_mul_f32 v[20:21], v[20:21], v[32:33] op_sel_hi:[1,0]
	v_pk_mul_f32 v[16:17], v[16:17], v[32:33] op_sel_hi:[1,0]
	v_pk_mul_f32 v[28:29], v[28:29], v[34:35]
	v_pk_mul_f32 v[18:19], v[18:19], v[32:33] op_sel_hi:[1,0]
	v_pk_mul_f32 v[24:25], v[24:25], v[28:29]
	v_pk_mul_f32 v[28:29], v[30:31], v[32:33] op_sel_hi:[1,0]
	s_nop 0
	v_mul_f32_e32 v30, 0xbfb8aa3b, v28
	v_mul_f32_e32 v31, 0xbfb8aa3b, v29
	v_exp_f32_e32 v30, v30
	v_exp_f32_e32 v31, v31
	v_add_f32_e32 v30, 1.0, v30
	v_add_f32_e32 v31, 1.0, v31
	v_rcp_f32_e32 v30, v30
	v_rcp_f32_e32 v31, v31
	s_nop 0
	v_pk_mul_f32 v[28:29], v[28:29], v[30:31]
	s_nop 0
	v_pk_mul_f32 v[26:27], v[26:27], v[28:29]
	v_mul_f32_e32 v28, 0xbfb8aa3b, v20
	v_mul_f32_e32 v29, 0xbfb8aa3b, v21
	v_exp_f32_e32 v28, v28
	v_exp_f32_e32 v29, v29
	v_add_f32_e32 v28, 1.0, v28
	v_add_f32_e32 v29, 1.0, v29
	v_rcp_f32_e32 v28, v28
	v_rcp_f32_e32 v29, v29
	s_nop 0
	v_pk_mul_f32 v[20:21], v[20:21], v[28:29]
	s_nop 0
	v_pk_mul_f32 v[20:21], v[16:17], v[20:21]
	v_pk_mul_f32 v[16:17], v[22:23], v[32:33] op_sel_hi:[1,0]
	v_add_u32_e32 v28, 0xa0, v138
	v_mul_f32_e32 v22, 0xbfb8aa3b, v16
	v_mul_f32_e32 v23, 0xbfb8aa3b, v17
	v_exp_f32_e32 v22, v22
	v_exp_f32_e32 v23, v23
	v_add_f32_e32 v22, 1.0, v22
	v_add_f32_e32 v23, 1.0, v23
	v_rcp_f32_e32 v22, v22
	v_rcp_f32_e32 v23, v23
	s_nop 0
	v_pk_mul_f32 v[16:17], v[16:17], v[22:23]
	s_nop 0
	v_pk_mul_f32 v[22:23], v[18:19], v[16:17]
	v_cvt_pk_bf16_f32 v18, v20, v21
	v_mad_i64_i32 v[20:21], s[18:19], v28, s11, v[116:117]
	v_cvt_pk_bf16_f32 v16, v24, v25
	v_cvt_pk_bf16_f32 v17, v26, v27
	v_cvt_pk_bf16_f32 v19, v22, v23
	v_lshl_add_u64 v[20:21], v[20:21], 0, v[118:119]
	global_store_dwordx4 v[20:21], v[16:19], off
	s_nop 1
	v_fmamk_f32 v16, v139, 0x3a800000, v226
	v_cmp_gt_f32_e32 vcc, s33, v16
	v_mul_f32_e32 v17, 0x4b800000, v16
	s_nop 0
	v_cndmask_b32_e32 v16, v16, v17, vcc
	v_rsq_f32_e32 v16, v16
	s_nop 0
	v_mul_f32_e32 v17, 0x45800000, v16
	v_cndmask_b32_e32 v16, v16, v17, vcc
	v_pk_mul_f32 v[12:13], v[12:13], v[16:17] op_sel_hi:[1,0]
	s_andn2_b64 vcc, exec, s[0:1]
	v_mul_f32_e32 v17, 0xbfb8aa3b, v12
	v_exp_f32_e32 v17, v17
	s_nop 0
	v_add_f32_e32 v17, 1.0, v17
	v_rcp_f32_e32 v18, v17
	v_pk_mul_f32 v[8:9], v[8:9], v[16:17] op_sel_hi:[1,0]
	v_mul_f32_e32 v17, 0xbfb8aa3b, v13
	v_exp_f32_e32 v17, v17
	s_nop 0
	v_add_f32_e32 v17, 1.0, v17
	v_rcp_f32_e32 v19, v17
	v_pk_mul_f32 v[10:11], v[10:11], v[16:17] op_sel_hi:[1,0]
	v_pk_mul_f32 v[4:5], v[4:5], v[16:17] op_sel_hi:[1,0]
	v_pk_mul_f32 v[0:1], v[0:1], v[16:17] op_sel_hi:[1,0]
	v_pk_mul_f32 v[12:13], v[12:13], v[18:19]
	v_pk_mul_f32 v[2:3], v[2:3], v[16:17] op_sel_hi:[1,0]
	v_pk_mul_f32 v[8:9], v[8:9], v[12:13]
	v_pk_mul_f32 v[12:13], v[14:15], v[16:17] op_sel_hi:[1,0]
	s_nop 0
	v_mul_f32_e32 v14, 0xbfb8aa3b, v12
	v_mul_f32_e32 v15, 0xbfb8aa3b, v13
	v_exp_f32_e32 v14, v14
	v_exp_f32_e32 v15, v15
	v_add_f32_e32 v14, 1.0, v14
	v_add_f32_e32 v15, 1.0, v15
	v_rcp_f32_e32 v14, v14
	v_rcp_f32_e32 v15, v15
	s_nop 0
	v_pk_mul_f32 v[12:13], v[12:13], v[14:15]
	s_nop 0
	v_pk_mul_f32 v[10:11], v[10:11], v[12:13]
	v_mul_f32_e32 v12, 0xbfb8aa3b, v4
	v_mul_f32_e32 v13, 0xbfb8aa3b, v5
	v_exp_f32_e32 v12, v12
	v_exp_f32_e32 v13, v13
	v_add_f32_e32 v12, 1.0, v12
	v_add_f32_e32 v13, 1.0, v13
	v_rcp_f32_e32 v12, v12
	v_rcp_f32_e32 v13, v13
	s_nop 0
	v_pk_mul_f32 v[4:5], v[4:5], v[12:13]
	s_nop 0
	v_pk_mul_f32 v[4:5], v[0:1], v[4:5]
	v_pk_mul_f32 v[0:1], v[6:7], v[16:17] op_sel_hi:[1,0]
	v_add_u32_e32 v12, 0xb0, v138
	v_mul_f32_e32 v6, 0xbfb8aa3b, v0
	v_mul_f32_e32 v7, 0xbfb8aa3b, v1
	v_exp_f32_e32 v6, v6
	v_exp_f32_e32 v7, v7
	v_add_f32_e32 v6, 1.0, v6
	v_add_f32_e32 v7, 1.0, v7
	v_rcp_f32_e32 v6, v6
	v_rcp_f32_e32 v7, v7
	s_nop 0
	v_pk_mul_f32 v[0:1], v[0:1], v[6:7]
	s_nop 0
	v_pk_mul_f32 v[6:7], v[2:3], v[0:1]
	v_cvt_pk_bf16_f32 v2, v4, v5
	v_mad_i64_i32 v[4:5], s[18:19], v12, s11, v[116:117]
	v_cvt_pk_bf16_f32 v0, v8, v9
	v_cvt_pk_bf16_f32 v1, v10, v11
	v_cvt_pk_bf16_f32 v3, v6, v7
	v_lshl_add_u64 v[4:5], v[4:5], 0, v[118:119]
	s_mov_b64 s[18:19], -1
	global_store_dwordx4 v[4:5], v[0:3], off
	s_cbranch_vccnz .LBB0_974
	s_andn2_b64 vcc, exec, s[2:3]
	s_cbranch_vccnz .LBB0_973
	s_barrier
	s_branch .LBB0_973
